# v028 + weight-conversion loads in the rwkv scan phase issued 8 at a time (less HBM contention for the co-running scan)
# speedup vs baseline: 1.0048x; 1.0048x over previous
; __device__ __forceinline__ void phase_wconv(const Frame& F, const Args& a, int l, unsigned char* wt, unsigned char* wth, int part) {
;     ...
;     for (int it = F.gw; it < NITEMS; it += F.NGW) {
;         int r = it;
;         if (r < I_A) {
;             const int m = r / I_FF, q = r % I_FF, f = m / 3, mm = m % 3;
;             if (!((f ? 2 : 1) & part)) continue;
;             if (mm < 2) {
;                 const float* W = a.in[F.z + (f ? 26 : 3) + mm] + (size_t)l * D * FF;
;                 const int kb = q / 176, nb = q % 176, n0 = 32 * nb;
;                 bf16* dst = (bf16*)(f ? wth + WO_UP2 : wt + WO_UP1);
;                 transpose_item(W, FF, 64 * kb, n0, dst, D, (n0 / 128) * 256 + mm * 128 + (n0 % 128), scr, F.lane);
;             } else {
;                 const float* W = a.in[F.z + (f ? 28 : 5)] + (size_t)l * FF * D;
;                 const int kb = q / 64, nb = q % 64, n0 = 32 * nb;
;                 bf16* dst = (bf16*)(f ? wth + WO_DN2 : wt + WO_DN1);
;                 transpose_item(W, D, 64 * kb, n0, dst, FF, n0, scr, F.lane);
;             }
;             continue;
;         }
;         r -= I_A;
;         if (r < I_IN) {
;             const float* W = a.in[F.z + 7] + (size_t)l * D * 15744;
;             const int kb = r / 492, nb = r % 492, n0 = 32 * nb;
;             if (!(((n0 >= 7680 && n0 < 9600) ? 1 : 2) & part)) continue;
;             bf16* dst; int row;
;             if (n0 < 4608) { dst = (bf16*)(wth + WO_ATT); row = n0; }
;             else if (n0 < 7680) { dst = (bf16*)(wth + WO_RET); row = n0 - 4608; }
;             else if (n0 < 9600) { dst = (bf16*)(wth + WO_CF); row = n0 - 7680; }
;             else { dst = (bf16*)(wth + WO_GATE); row = n0 - 9600; }
;             transpose_item(W, 15744, 64 * kb, n0, dst, D, row, scr, F.lane);
;             continue;
;         }
;         r -= I_IN;
;         if (!(part & 2)) break;
;         if (r < I_BA) { const int kb = r / 64, nb = r % 64; transpose_item(a.in[F.z + 21] + (size_t)l * 512 * D, D, 64 * kb, 32 * nb, (bf16*)(wth + WO_BA), 512, 32 * nb, scr, F.lane); continue; }
;         r -= I_BA;
;         if (r < I_BB) { const int kb = r / 64, nb = r % 64; transpose_item(a.in[F.z + 22] + (size_t)l * 1024 * D, D, 64 * kb, 32 * nb, (bf16*)(wth + WO_BB), 1024, 32 * nb, scr, F.lane); continue; }
;         r -= I_BB;
.LBB0_703:
	s_cmp_gt_i32 s30, 0x83ff
	s_mov_b64 s[16:17], -1
	s_cbranch_scc0 .LBB0_731
	s_cmpk_gt_u32 s30, 0xc17f
	s_cbranch_scc0 .LBB0_718
	s_cmpk_gt_u32 s30, 0xc37f
	s_cbranch_scc0 .LBB0_715
	s_cmpk_gt_u32 s30, 0xc77f
	s_cbranch_scc0 .LBB0_712
	s_and_b32 s18, s28, 0x7e0
	s_cmpk_gt_u32 s30, 0xc97f
	v_or_b32_e32 v28, s18, v21
	v_or_b32_e32 v27, s18, v23
	v_or_b32_e32 v26, s18, v24
	v_or_b32_e32 v15, s18, v25
	s_cbranch_scc0 .LBB0_709
	s_and_b32 s16, s30, 0x7fffffc0
	s_add_i32 s82, s16, 0xffff3680
	s_load_dwordx2 s[16:17], s[14:15], 0xc0
	v_readlane_b32 s20, v254, 48
	v_readlane_b32 s21, v254, 49
	v_or_b32_e32 v16, s82, v1
	v_lshlrev_b32_e32 v184, 2, v0
	s_waitcnt lgkmcnt(0)
	s_add_u32 s16, s16, s20
	s_addc_u32 s17, s17, s21
	s_lshl_b32 s19, s18, 2
	s_add_u32 s16, s16, s19
	s_addc_u32 s17, s17, 0
	v_mov_b32_e32 v17, v185
	v_lshl_add_u64 v[18:19], s[16:17], 0, v[184:185]
	v_lshlrev_b64 v[30:31], 13, v[16:17]
	v_lshl_add_u64 v[30:31], v[18:19], 0, v[30:31]
	v_or_b32_e32 v184, 2, v16
	global_load_dword v29, v[30:31], off
	v_lshlrev_b64 v[30:31], 13, v[184:185]
	v_lshl_add_u64 v[30:31], v[18:19], 0, v[30:31]
	v_or_b32_e32 v184, 4, v16
	global_load_dword v32, v[30:31], off
	v_lshlrev_b64 v[30:31], 13, v[184:185]
	v_lshl_add_u64 v[30:31], v[18:19], 0, v[30:31]
	v_or_b32_e32 v184, 6, v16
	global_load_dword v33, v[30:31], off
	v_lshlrev_b64 v[30:31], 13, v[184:185]
	v_lshl_add_u64 v[30:31], v[18:19], 0, v[30:31]
	v_or_b32_e32 v184, 8, v16
	global_load_dword v34, v[30:31], off
	v_lshlrev_b64 v[30:31], 13, v[184:185]
	v_lshl_add_u64 v[30:31], v[18:19], 0, v[30:31]
	v_or_b32_e32 v184, 10, v16
	global_load_dword v35, v[30:31], off
	v_lshlrev_b64 v[30:31], 13, v[184:185]
	v_lshl_add_u64 v[30:31], v[18:19], 0, v[30:31]
	v_or_b32_e32 v184, 12, v16
	global_load_dword v36, v[30:31], off
	v_lshlrev_b64 v[30:31], 13, v[184:185]
	v_lshl_add_u64 v[30:31], v[18:19], 0, v[30:31]
	v_or_b32_e32 v184, 14, v16
	global_load_dword v37, v[30:31], off
	v_lshlrev_b64 v[30:31], 13, v[184:185]
	v_lshl_add_u64 v[30:31], v[18:19], 0, v[30:31]
	v_or_b32_e32 v184, 16, v16
	global_load_dword v38, v[30:31], off
	s_waitcnt vmcnt(2)
	v_lshlrev_b64 v[30:31], 13, v[184:185]
	v_lshl_add_u64 v[30:31], v[18:19], 0, v[30:31]
	v_or_b32_e32 v184, 18, v16
	global_load_dword v39, v[30:31], off
	v_lshlrev_b64 v[30:31], 13, v[184:185]
	v_lshl_add_u64 v[30:31], v[18:19], 0, v[30:31]
	v_or_b32_e32 v184, 20, v16
	global_load_dword v40, v[30:31], off
	v_lshlrev_b64 v[30:31], 13, v[184:185]
	v_lshl_add_u64 v[30:31], v[18:19], 0, v[30:31]
	v_or_b32_e32 v184, 22, v16
	global_load_dword v41, v[30:31], off
	v_lshlrev_b64 v[30:31], 13, v[184:185]
	v_lshl_add_u64 v[30:31], v[18:19], 0, v[30:31]
	v_or_b32_e32 v184, 24, v16
	global_load_dword v42, v[30:31], off
	v_lshlrev_b64 v[30:31], 13, v[184:185]
	v_lshl_add_u64 v[30:31], v[18:19], 0, v[30:31]
	v_or_b32_e32 v184, 26, v16
	global_load_dword v43, v[30:31], off
	v_lshlrev_b64 v[30:31], 13, v[184:185]
	v_lshl_add_u64 v[30:31], v[18:19], 0, v[30:31]
	v_or_b32_e32 v184, 28, v16
	global_load_dword v44, v[30:31], off
	v_lshlrev_b64 v[30:31], 13, v[184:185]
	v_lshl_add_u64 v[30:31], v[18:19], 0, v[30:31]
	v_or_b32_e32 v184, 30, v16
	global_load_dword v45, v[30:31], off
	v_lshlrev_b64 v[30:31], 13, v[184:185]
	v_lshl_add_u64 v[30:31], v[18:19], 0, v[30:31]
	v_or_b32_e32 v184, 32, v16
	global_load_dword v46, v[30:31], off
	s_waitcnt vmcnt(2)
	v_lshlrev_b64 v[30:31], 13, v[184:185]
	v_lshl_add_u64 v[30:31], v[18:19], 0, v[30:31]
	v_or_b32_e32 v184, 34, v16
	global_load_dword v47, v[30:31], off
	v_lshlrev_b64 v[30:31], 13, v[184:185]
	v_lshl_add_u64 v[30:31], v[18:19], 0, v[30:31]
	v_or_b32_e32 v184, 36, v16
	global_load_dword v48, v[30:31], off
	v_lshlrev_b64 v[30:31], 13, v[184:185]
	v_lshl_add_u64 v[30:31], v[18:19], 0, v[30:31]
	v_or_b32_e32 v184, 38, v16
	global_load_dword v49, v[30:31], off
	v_lshlrev_b64 v[30:31], 13, v[184:185]
	v_lshl_add_u64 v[30:31], v[18:19], 0, v[30:31]
	v_or_b32_e32 v184, 40, v16
	global_load_dword v50, v[30:31], off
	v_lshlrev_b64 v[30:31], 13, v[184:185]
	v_lshl_add_u64 v[30:31], v[18:19], 0, v[30:31]
	v_or_b32_e32 v184, 42, v16
	global_load_dword v51, v[30:31], off
	v_lshlrev_b64 v[30:31], 13, v[184:185]
	v_lshl_add_u64 v[30:31], v[18:19], 0, v[30:31]
	v_or_b32_e32 v184, 44, v16
	global_load_dword v52, v[30:31], off
	v_lshlrev_b64 v[30:31], 13, v[184:185]
	v_lshl_add_u64 v[30:31], v[18:19], 0, v[30:31]
	v_or_b32_e32 v184, 46, v16
	global_load_dword v53, v[30:31], off
	v_lshlrev_b64 v[30:31], 13, v[184:185]
	v_lshl_add_u64 v[30:31], v[18:19], 0, v[30:31]
	v_or_b32_e32 v184, 48, v16
	global_load_dword v54, v[30:31], off
	s_waitcnt vmcnt(2)
	v_lshlrev_b64 v[30:31], 13, v[184:185]
	v_lshl_add_u64 v[30:31], v[18:19], 0, v[30:31]
	v_or_b32_e32 v184, 50, v16
	global_load_dword v55, v[30:31], off
	v_lshlrev_b64 v[30:31], 13, v[184:185]
	v_lshl_add_u64 v[30:31], v[18:19], 0, v[30:31]
	v_or_b32_e32 v184, 52, v16
	global_load_dword v56, v[30:31], off
	v_lshlrev_b64 v[30:31], 13, v[184:185]
	v_lshl_add_u64 v[30:31], v[18:19], 0, v[30:31]
	v_or_b32_e32 v184, 54, v16
	global_load_dword v57, v[30:31], off
	v_lshlrev_b64 v[30:31], 13, v[184:185]
	v_lshl_add_u64 v[30:31], v[18:19], 0, v[30:31]
	v_or_b32_e32 v184, 56, v16
	global_load_dword v58, v[30:31], off
	v_lshlrev_b64 v[30:31], 13, v[184:185]
	v_lshl_add_u64 v[30:31], v[18:19], 0, v[30:31]
	v_or_b32_e32 v184, 58, v16
	global_load_dword v59, v[30:31], off
	v_lshlrev_b64 v[30:31], 13, v[184:185]
	v_lshl_add_u64 v[30:31], v[18:19], 0, v[30:31]
	v_or_b32_e32 v184, 60, v16
	global_load_dword v60, v[30:31], off
	v_lshlrev_b64 v[30:31], 13, v[184:185]
	v_or_b32_e32 v184, 62, v16
	v_lshlrev_b64 v[16:17], 13, v[184:185]
	v_lshl_add_u64 v[30:31], v[18:19], 0, v[30:31]
	v_lshl_add_u64 v[16:17], v[18:19], 0, v[16:17]
	global_load_dword v30, v[30:31], off
	v_lshlrev_b32_e32 v184, 12, v28
	global_load_dword v16, v[16:17], off
	v_add_u32_e32 v17, 0x400, v20
	s_waitcnt vmcnt(30)
; #define LAS __attribute__((address_space(3)))
; #define LDS_WAIT() asm volatile("s_waitcnt lgkmcnt(0)" ::: "memory")
; __device__ __forceinline__ unsigned pk2(float lo, float hi) { return cvt_pk_bf16(lo, hi); }
; __device__ __forceinline__ void transpose_item(const float* W, int ldw, int k0, int n0, bf16* WT, int Kdst, int dst_row0, LAS float* scr, int lane) {
;     ...
;     for (int i = 0; i < 32; ++i) { const int kk = 2 * i + (lane >> 5); scr[kk * 33 + (lane & 31)] = tv[i]; }
;     LDS_WAIT(); asm volatile("" ::: "memory");
;     const int c = lane & 7;
; #pragma unroll
;     for (int j = 0; j < 4; ++j) { const int n = (lane >> 3) + 8 * j; const LAS float* s = scr + (8 * c) * 33 + n;
;         v4u o; o.x = pk2(s[0 * 33], s[1 * 33]); o.y = pk2(s[2 * 33], s[3 * 33]); o.z = pk2(s[4 * 33], s[5 * 33]); o.w = pk2(s[6 * 33], s[7 * 33]);
;         *(v4u*)(WT + (size_t)(dst_row0 + n) * Kdst + k0 + 8 * c) = o; }
; __device__ __forceinline__ void phase_wconv(const Frame& F, const Args& a, int l, unsigned char* wt, unsigned char* wth, int part) {
;     ...
;         if (r < I_BC) { const int kb = r / 64, nb = r % 64; transpose_item(a.in[F.z + 23] + (size_t)l * 512 * D, D, 64 * kb, 32 * nb, (bf16*)(wth + WO_BC), 512, 32 * nb, scr, F.lane); continue; }
	ds_write2_b32 v20, v29, v32 offset1:66
	s_waitcnt vmcnt(28)
	ds_write2_b32 v20, v33, v34 offset0:132 offset1:198
	s_waitcnt vmcnt(26)
	ds_write2_b32 v17, v35, v36 offset0:8 offset1:74
	s_waitcnt vmcnt(24)
	ds_write2_b32 v17, v37, v38 offset0:140 offset1:206
	v_add_u32_e32 v17, 0x800, v20
	s_waitcnt vmcnt(22)
	ds_write2_b32 v17, v39, v40 offset0:16 offset1:82
	s_waitcnt vmcnt(20)
	ds_write2_b32 v17, v41, v42 offset0:148 offset1:214
	v_add_u32_e32 v17, 0xc00, v20
	s_waitcnt vmcnt(18)
	ds_write2_b32 v17, v43, v44 offset0:24 offset1:90
	s_waitcnt vmcnt(16)
	ds_write2_b32 v17, v45, v46 offset0:156 offset1:222
	v_add_u32_e32 v17, 0x1000, v20
	s_waitcnt vmcnt(14)
	ds_write2_b32 v17, v47, v48 offset0:32 offset1:98
	s_waitcnt vmcnt(12)
	ds_write2_b32 v17, v49, v50 offset0:164 offset1:230
	v_add_u32_e32 v17, 0x1400, v20
	s_waitcnt vmcnt(10)
	ds_write2_b32 v17, v51, v52 offset0:40 offset1:106
	s_waitcnt vmcnt(8)
	ds_write2_b32 v17, v53, v54 offset0:172 offset1:238
	v_add_u32_e32 v17, 0x1800, v20
	s_waitcnt vmcnt(6)
	ds_write2_b32 v17, v55, v56 offset0:48 offset1:114
	s_waitcnt vmcnt(4)
	ds_write2_b32 v17, v57, v58 offset0:180 offset1:246
	v_add_u32_e32 v17, 0x1c00, v20
	s_waitcnt vmcnt(2)
	ds_write2_b32 v17, v59, v60 offset0:56 offset1:122
	s_waitcnt vmcnt(0)
	ds_write2_b32 v17, v30, v16 offset0:188 offset1:254
	s_waitcnt lgkmcnt(0)
	ds_read2_b32 v[32:33], v22 offset0:33 offset1:41
	ds_read2_b32 v[34:35], v22 offset1:8
	ds_read2_b32 v[36:37], v22 offset0:66 offset1:74
	ds_read2_b32 v[38:39], v22 offset0:99 offset1:107
	ds_read2_b32 v[40:41], v22 offset0:132 offset1:140
	ds_read2_b32 v[42:43], v22 offset0:165 offset1:173
	ds_read2_b32 v[44:45], v22 offset0:198 offset1:206
	ds_read2_b32 v[46:47], v22 offset0:231 offset1:239
	v_lshl_add_u64 v[30:31], s[82:83], 1, v[2:3]
	s_waitcnt lgkmcnt(6)
	v_cvt_pk_bf16_f32 v16, v34, v32
	s_waitcnt lgkmcnt(4)
	v_cvt_pk_bf16_f32 v17, v36, v38
	s_waitcnt lgkmcnt(2)
	v_cvt_pk_bf16_f32 v18, v40, v42
	s_waitcnt lgkmcnt(0)
	v_cvt_pk_bf16_f32 v19, v44, v46
	v_lshl_add_u64 v[48:49], v[30:31], 0, v[184:185]
	v_lshlrev_b32_e32 v184, 12, v27
	global_store_dwordx4 v[48:49], v[16:19], off
	s_mov_b64 s[16:17], 0
	s_nop 0
	v_cvt_pk_bf16_f32 v16, v35, v33
	v_cvt_pk_bf16_f32 v17, v37, v39
	v_cvt_pk_bf16_f32 v18, v41, v43
	v_cvt_pk_bf16_f32 v19, v45, v47
	v_lshl_add_u64 v[32:33], v[30:31], 0, v[184:185]
	global_store_dwordx4 v[32:33], v[16:19], off
	ds_read2_b32 v[32:33], v22 offset0:49 offset1:57
	ds_read2_b32 v[34:35], v22 offset0:16 offset1:24
	ds_read2_b32 v[36:37], v22 offset0:82 offset1:90
	ds_read2_b32 v[38:39], v22 offset0:115 offset1:123
	ds_read2_b32 v[40:41], v22 offset0:148 offset1:156
	ds_read2_b32 v[42:43], v22 offset0:181 offset1:189
	ds_read2_b32 v[44:45], v22 offset0:214 offset1:222
	ds_read2_b32 v[46:47], v22 offset0:247 offset1:255
	v_lshlrev_b32_e32 v184, 12, v26
	s_waitcnt lgkmcnt(6)
	v_cvt_pk_bf16_f32 v16, v34, v32
	s_waitcnt lgkmcnt(4)
	v_cvt_pk_bf16_f32 v17, v36, v38
	s_waitcnt lgkmcnt(2)
	v_cvt_pk_bf16_f32 v18, v40, v42
	s_waitcnt lgkmcnt(0)
	v_cvt_pk_bf16_f32 v19, v44, v46
	v_lshl_add_u64 v[48:49], v[30:31], 0, v[184:185]
	v_lshlrev_b32_e32 v184, 12, v15
	global_store_dwordx4 v[48:49], v[16:19], off
	v_lshl_add_u64 v[30:31], v[30:31], 0, v[184:185]
	s_nop 0
	v_cvt_pk_bf16_f32 v16, v35, v33
	v_cvt_pk_bf16_f32 v17, v37, v39
	v_cvt_pk_bf16_f32 v18, v41, v43
	v_cvt_pk_bf16_f32 v19, v45, v47
	global_store_dwordx4 v[30:31], v[16:19], off
	s_waitcnt lgkmcnt(0)
.LBB0_709:
	s_andn2_b64 vcc, exec, s[16:17]
	s_cbranch_vccnz .LBB0_711
	s_and_b32 s16, s30, 0xffc0
	s_add_i32 s82, s16, 0xffff3880
	s_load_dwordx2 s[16:17], s[14:15], 0xb8
	v_readlane_b32 s20, v254, 36
	v_readlane_b32 s21, v254, 37
	s_lshl_b64 s[20:21], s[20:21], 2
	v_or_b32_e32 v16, s82, v1
	s_waitcnt lgkmcnt(0)
	s_add_u32 s16, s16, s20
	s_addc_u32 s17, s17, s21
	s_lshl_b32 s18, s18, 2
	s_add_u32 s16, s16, s18
	s_addc_u32 s17, s17, 0
	v_lshlrev_b32_e32 v184, 2, v0
	v_mov_b32_e32 v17, v185
	v_lshl_add_u64 v[18:19], s[16:17], 0, v[184:185]
	v_lshlrev_b64 v[30:31], 13, v[16:17]
	v_lshl_add_u64 v[30:31], v[18:19], 0, v[30:31]
	v_or_b32_e32 v184, 2, v16
	global_load_dword v29, v[30:31], off
	v_lshlrev_b64 v[30:31], 13, v[184:185]
	v_lshl_add_u64 v[30:31], v[18:19], 0, v[30:31]
	v_or_b32_e32 v184, 4, v16
	global_load_dword v32, v[30:31], off
	v_lshlrev_b64 v[30:31], 13, v[184:185]
	v_lshl_add_u64 v[30:31], v[18:19], 0, v[30:31]
	v_or_b32_e32 v184, 6, v16
	global_load_dword v33, v[30:31], off
	v_lshlrev_b64 v[30:31], 13, v[184:185]
	v_lshl_add_u64 v[30:31], v[18:19], 0, v[30:31]
	v_or_b32_e32 v184, 8, v16
	global_load_dword v34, v[30:31], off
	v_lshlrev_b64 v[30:31], 13, v[184:185]
	v_lshl_add_u64 v[30:31], v[18:19], 0, v[30:31]
	v_or_b32_e32 v184, 10, v16
	global_load_dword v35, v[30:31], off
	v_lshlrev_b64 v[30:31], 13, v[184:185]
	v_lshl_add_u64 v[30:31], v[18:19], 0, v[30:31]
	v_or_b32_e32 v184, 12, v16
	global_load_dword v36, v[30:31], off
	v_lshlrev_b64 v[30:31], 13, v[184:185]
	v_lshl_add_u64 v[30:31], v[18:19], 0, v[30:31]
	v_or_b32_e32 v184, 14, v16
	global_load_dword v37, v[30:31], off
	v_lshlrev_b64 v[30:31], 13, v[184:185]
	v_lshl_add_u64 v[30:31], v[18:19], 0, v[30:31]
	v_or_b32_e32 v184, 16, v16
	global_load_dword v38, v[30:31], off
	s_waitcnt vmcnt(2)
; #define LAS __attribute__((address_space(3)))
; __device__ __forceinline__ void transpose_item(const float* W, int ldw, int k0, int n0, bf16* WT, int Kdst, int dst_row0, LAS float* scr, int lane) {
;     float tv[32];
; #pragma unroll
;     for (int i = 0; i < 32; ++i) { const int kk = 2 * i + (lane >> 5); tv[i] = W[(size_t)(k0 + kk) * ldw + n0 + (lane & 31)]; }
	v_lshlrev_b64 v[30:31], 13, v[184:185]
	v_lshl_add_u64 v[30:31], v[18:19], 0, v[30:31]
	v_or_b32_e32 v184, 18, v16
	global_load_dword v39, v[30:31], off
	v_lshlrev_b64 v[30:31], 13, v[184:185]
	v_lshl_add_u64 v[30:31], v[18:19], 0, v[30:31]
	v_or_b32_e32 v184, 20, v16
	global_load_dword v40, v[30:31], off
	v_lshlrev_b64 v[30:31], 13, v[184:185]
	v_lshl_add_u64 v[30:31], v[18:19], 0, v[30:31]
	v_or_b32_e32 v184, 22, v16
	global_load_dword v41, v[30:31], off
	v_lshlrev_b64 v[30:31], 13, v[184:185]
	v_lshl_add_u64 v[30:31], v[18:19], 0, v[30:31]
	v_or_b32_e32 v184, 24, v16
	global_load_dword v42, v[30:31], off
	v_lshlrev_b64 v[30:31], 13, v[184:185]
	v_lshl_add_u64 v[30:31], v[18:19], 0, v[30:31]
	v_or_b32_e32 v184, 26, v16
	global_load_dword v43, v[30:31], off
	v_lshlrev_b64 v[30:31], 13, v[184:185]
	v_lshl_add_u64 v[30:31], v[18:19], 0, v[30:31]
	v_or_b32_e32 v184, 28, v16
	global_load_dword v44, v[30:31], off
	v_lshlrev_b64 v[30:31], 13, v[184:185]
	v_lshl_add_u64 v[30:31], v[18:19], 0, v[30:31]
	v_or_b32_e32 v184, 30, v16
	global_load_dword v45, v[30:31], off
	v_lshlrev_b64 v[30:31], 13, v[184:185]
	v_lshl_add_u64 v[30:31], v[18:19], 0, v[30:31]
	v_or_b32_e32 v184, 32, v16
	global_load_dword v46, v[30:31], off
	s_waitcnt vmcnt(2)
	v_lshlrev_b64 v[30:31], 13, v[184:185]
	v_lshl_add_u64 v[30:31], v[18:19], 0, v[30:31]
	v_or_b32_e32 v184, 34, v16
	global_load_dword v47, v[30:31], off
	v_lshlrev_b64 v[30:31], 13, v[184:185]
	v_lshl_add_u64 v[30:31], v[18:19], 0, v[30:31]
	v_or_b32_e32 v184, 36, v16
	global_load_dword v48, v[30:31], off
	v_lshlrev_b64 v[30:31], 13, v[184:185]
	v_lshl_add_u64 v[30:31], v[18:19], 0, v[30:31]
	v_or_b32_e32 v184, 38, v16
	global_load_dword v49, v[30:31], off
	v_lshlrev_b64 v[30:31], 13, v[184:185]
	v_lshl_add_u64 v[30:31], v[18:19], 0, v[30:31]
	v_or_b32_e32 v184, 40, v16
	global_load_dword v50, v[30:31], off
	v_lshlrev_b64 v[30:31], 13, v[184:185]
	v_lshl_add_u64 v[30:31], v[18:19], 0, v[30:31]
	v_or_b32_e32 v184, 42, v16
	global_load_dword v51, v[30:31], off
	v_lshlrev_b64 v[30:31], 13, v[184:185]
	v_lshl_add_u64 v[30:31], v[18:19], 0, v[30:31]
	v_or_b32_e32 v184, 44, v16
	global_load_dword v52, v[30:31], off
	v_lshlrev_b64 v[30:31], 13, v[184:185]
	v_lshl_add_u64 v[30:31], v[18:19], 0, v[30:31]
	v_or_b32_e32 v184, 46, v16
	global_load_dword v53, v[30:31], off
	v_lshlrev_b64 v[30:31], 13, v[184:185]
	v_lshl_add_u64 v[30:31], v[18:19], 0, v[30:31]
	v_or_b32_e32 v184, 48, v16
	global_load_dword v54, v[30:31], off
	s_waitcnt vmcnt(2)
	v_lshlrev_b64 v[30:31], 13, v[184:185]
	v_lshl_add_u64 v[30:31], v[18:19], 0, v[30:31]
	v_or_b32_e32 v184, 50, v16
	global_load_dword v55, v[30:31], off
	v_lshlrev_b64 v[30:31], 13, v[184:185]
	v_lshl_add_u64 v[30:31], v[18:19], 0, v[30:31]
	v_or_b32_e32 v184, 52, v16
	global_load_dword v56, v[30:31], off
	v_lshlrev_b64 v[30:31], 13, v[184:185]
	v_lshl_add_u64 v[30:31], v[18:19], 0, v[30:31]
	v_or_b32_e32 v184, 54, v16
	global_load_dword v57, v[30:31], off
	v_lshlrev_b64 v[30:31], 13, v[184:185]
	v_lshl_add_u64 v[30:31], v[18:19], 0, v[30:31]
	v_or_b32_e32 v184, 56, v16
	global_load_dword v58, v[30:31], off
	v_lshlrev_b64 v[30:31], 13, v[184:185]
	v_lshl_add_u64 v[30:31], v[18:19], 0, v[30:31]
	v_or_b32_e32 v184, 58, v16
	global_load_dword v59, v[30:31], off
	v_lshlrev_b64 v[30:31], 13, v[184:185]
	v_lshl_add_u64 v[30:31], v[18:19], 0, v[30:31]
	v_or_b32_e32 v184, 60, v16
	global_load_dword v60, v[30:31], off
	v_lshlrev_b64 v[30:31], 13, v[184:185]
	v_or_b32_e32 v184, 62, v16
	v_lshlrev_b64 v[16:17], 13, v[184:185]
	v_lshl_add_u64 v[30:31], v[18:19], 0, v[30:31]
	v_lshl_add_u64 v[16:17], v[18:19], 0, v[16:17]
	global_load_dword v30, v[30:31], off
	v_lshlrev_b32_e32 v184, 10, v28
	global_load_dword v16, v[16:17], off
	v_add_u32_e32 v17, 0x400, v20
	s_waitcnt vmcnt(30)
; #define LAS __attribute__((address_space(3)))
; #define LDS_WAIT() asm volatile("s_waitcnt lgkmcnt(0)" ::: "memory")
; __device__ __forceinline__ unsigned pk2(float lo, float hi) { return cvt_pk_bf16(lo, hi); }
; __device__ __forceinline__ void transpose_item(const float* W, int ldw, int k0, int n0, bf16* WT, int Kdst, int dst_row0, LAS float* scr, int lane) {
;     ...
;     for (int i = 0; i < 32; ++i) { const int kk = 2 * i + (lane >> 5); scr[kk * 33 + (lane & 31)] = tv[i]; }
;     LDS_WAIT(); asm volatile("" ::: "memory");
;     const int c = lane & 7;
; #pragma unroll
;     for (int j = 0; j < 4; ++j) { const int n = (lane >> 3) + 8 * j; const LAS float* s = scr + (8 * c) * 33 + n;
;         v4u o; o.x = pk2(s[0 * 33], s[1 * 33]); o.y = pk2(s[2 * 33], s[3 * 33]); o.z = pk2(s[4 * 33], s[5 * 33]); o.w = pk2(s[6 * 33], s[7 * 33]);
;         *(v4u*)(WT + (size_t)(dst_row0 + n) * Kdst + k0 + 8 * c) = o; }
;     LDS_WAIT(); asm volatile("" ::: "memory");
	ds_write2_b32 v20, v29, v32 offset1:66
	s_waitcnt vmcnt(28)
	ds_write2_b32 v20, v33, v34 offset0:132 offset1:198
	s_waitcnt vmcnt(26)
	ds_write2_b32 v17, v35, v36 offset0:8 offset1:74
	s_waitcnt vmcnt(24)
	ds_write2_b32 v17, v37, v38 offset0:140 offset1:206
	v_add_u32_e32 v17, 0x800, v20
	s_waitcnt vmcnt(22)
	ds_write2_b32 v17, v39, v40 offset0:16 offset1:82
	s_waitcnt vmcnt(20)
	ds_write2_b32 v17, v41, v42 offset0:148 offset1:214
	v_add_u32_e32 v17, 0xc00, v20
	s_waitcnt vmcnt(18)
	ds_write2_b32 v17, v43, v44 offset0:24 offset1:90
	s_waitcnt vmcnt(16)
	ds_write2_b32 v17, v45, v46 offset0:156 offset1:222
	v_add_u32_e32 v17, 0x1000, v20
	s_waitcnt vmcnt(14)
	ds_write2_b32 v17, v47, v48 offset0:32 offset1:98
	s_waitcnt vmcnt(12)
	ds_write2_b32 v17, v49, v50 offset0:164 offset1:230
	v_add_u32_e32 v17, 0x1400, v20
	s_waitcnt vmcnt(10)
	ds_write2_b32 v17, v51, v52 offset0:40 offset1:106
	s_waitcnt vmcnt(8)
	ds_write2_b32 v17, v53, v54 offset0:172 offset1:238
	v_add_u32_e32 v17, 0x1800, v20
	s_waitcnt vmcnt(6)
	ds_write2_b32 v17, v55, v56 offset0:48 offset1:114
	s_waitcnt vmcnt(4)
	ds_write2_b32 v17, v57, v58 offset0:180 offset1:246
	v_add_u32_e32 v17, 0x1c00, v20
	s_waitcnt vmcnt(2)
	ds_write2_b32 v17, v59, v60 offset0:56 offset1:122
	s_waitcnt vmcnt(0)
	ds_write2_b32 v17, v30, v16 offset0:188 offset1:254
	s_waitcnt lgkmcnt(0)
	ds_read2_b32 v[32:33], v22 offset0:33 offset1:41
	ds_read2_b32 v[34:35], v22 offset1:8
	ds_read2_b32 v[36:37], v22 offset0:66 offset1:74
	ds_read2_b32 v[38:39], v22 offset0:99 offset1:107
	ds_read2_b32 v[40:41], v22 offset0:132 offset1:140
	ds_read2_b32 v[42:43], v22 offset0:165 offset1:173
	ds_read2_b32 v[44:45], v22 offset0:198 offset1:206
	ds_read2_b32 v[46:47], v22 offset0:231 offset1:239
	v_lshl_add_u64 v[30:31], s[82:83], 1, v[4:5]
	s_waitcnt lgkmcnt(6)
	v_cvt_pk_bf16_f32 v16, v34, v32
	s_waitcnt lgkmcnt(4)
	v_cvt_pk_bf16_f32 v17, v36, v38
	s_waitcnt lgkmcnt(2)
	v_cvt_pk_bf16_f32 v18, v40, v42
	s_waitcnt lgkmcnt(0)
	v_cvt_pk_bf16_f32 v19, v44, v46
	v_lshl_add_u64 v[28:29], v[30:31], 0, v[184:185]
	v_lshlrev_b32_e32 v184, 10, v27
	global_store_dwordx4 v[28:29], v[16:19], off
	v_lshl_add_u64 v[28:29], v[30:31], 0, v[184:185]
	v_lshlrev_b32_e32 v184, 10, v26
	v_cvt_pk_bf16_f32 v16, v35, v33
	v_cvt_pk_bf16_f32 v17, v37, v39
	v_cvt_pk_bf16_f32 v18, v41, v43
	v_cvt_pk_bf16_f32 v19, v45, v47
	global_store_dwordx4 v[28:29], v[16:19], off
	ds_read2_b32 v[28:29], v22 offset0:49 offset1:57
	ds_read2_b32 v[32:33], v22 offset0:16 offset1:24
	ds_read2_b32 v[34:35], v22 offset0:82 offset1:90
	ds_read2_b32 v[36:37], v22 offset0:115 offset1:123
	ds_read2_b32 v[38:39], v22 offset0:148 offset1:156
	ds_read2_b32 v[40:41], v22 offset0:181 offset1:189
	ds_read2_b32 v[42:43], v22 offset0:214 offset1:222
	ds_read2_b32 v[44:45], v22 offset0:247 offset1:255
	v_lshl_add_u64 v[26:27], v[30:31], 0, v[184:185]
	s_waitcnt lgkmcnt(6)
	v_cvt_pk_bf16_f32 v16, v32, v28
	s_waitcnt lgkmcnt(4)
	v_cvt_pk_bf16_f32 v17, v34, v36
	s_waitcnt lgkmcnt(2)
	v_cvt_pk_bf16_f32 v18, v38, v40
	s_waitcnt lgkmcnt(0)
	v_cvt_pk_bf16_f32 v19, v42, v44
	v_lshlrev_b32_e32 v184, 10, v15
	global_store_dwordx4 v[26:27], v[16:19], off
	v_lshl_add_u64 v[26:27], v[30:31], 0, v[184:185]
	s_nop 0
	v_cvt_pk_bf16_f32 v16, v33, v29
	v_cvt_pk_bf16_f32 v17, v35, v37
	v_cvt_pk_bf16_f32 v18, v39, v41
	v_cvt_pk_bf16_f32 v19, v43, v45
	global_store_dwordx4 v[26:27], v[16:19], off
	s_waitcnt lgkmcnt(0)

; #define LAS __attribute__((address_space(3)))
; __device__ __forceinline__ void transpose_item(const float* W, int ldw, int k0, int n0, bf16* WT, int Kdst, int dst_row0, LAS float* scr, int lane) {
;     float tv[32];
; #pragma unroll
;     for (int i = 0; i < 32; ++i) { const int kk = 2 * i + (lane >> 5); tv[i] = W[(size_t)(k0 + kk) * ldw + n0 + (lane & 31)]; }
; __device__ __forceinline__ void phase_wconv(const Frame& F, const Args& a, int l, unsigned char* wt, unsigned char* wth, int part) {
;     ...
;         if (r < I_BB) { const int kb = r / 64, nb = r % 64; transpose_item(a.in[F.z + 22] + (size_t)l * 1024 * D, D, 64 * kb, 32 * nb, (bf16*)(wth + WO_BB), 1024, 32 * nb, scr, F.lane); continue; }
.LBB0_712:
	s_andn2_b64 vcc, exec, s[16:17]
	s_cbranch_vccnz .LBB0_714
	s_and_b32 s16, s30, 0xffc0
	s_add_i32 s82, s16, 0xffff3c80
	s_load_dwordx2 s[16:17], s[14:15], 0xb0
	v_readlane_b32 s18, v254, 50
	v_readlane_b32 s19, v254, 51
	v_or_b32_e32 v16, s82, v1
	v_lshlrev_b32_e32 v184, 2, v0
	s_waitcnt lgkmcnt(0)
	s_add_u32 s18, s16, s18
	s_addc_u32 s17, s17, s19
	s_and_b32 s16, s28, 0x7e0
	s_lshl_b32 s19, s16, 2
	s_add_u32 s18, s18, s19
	s_addc_u32 s19, s17, 0
	v_mov_b32_e32 v17, v185
	v_lshl_add_u64 v[18:19], s[18:19], 0, v[184:185]
	v_lshlrev_b64 v[26:27], 13, v[16:17]
	v_lshl_add_u64 v[26:27], v[18:19], 0, v[26:27]
	v_or_b32_e32 v184, 2, v16
	global_load_dword v15, v[26:27], off
	v_lshlrev_b64 v[26:27], 13, v[184:185]
	v_lshl_add_u64 v[26:27], v[18:19], 0, v[26:27]
	v_or_b32_e32 v184, 4, v16
	global_load_dword v28, v[26:27], off
	v_lshlrev_b64 v[26:27], 13, v[184:185]
	v_lshl_add_u64 v[26:27], v[18:19], 0, v[26:27]
	v_or_b32_e32 v184, 6, v16
	global_load_dword v29, v[26:27], off
	v_lshlrev_b64 v[26:27], 13, v[184:185]
	v_lshl_add_u64 v[26:27], v[18:19], 0, v[26:27]
	v_or_b32_e32 v184, 8, v16
	global_load_dword v30, v[26:27], off
	v_lshlrev_b64 v[26:27], 13, v[184:185]
	v_lshl_add_u64 v[26:27], v[18:19], 0, v[26:27]
	v_or_b32_e32 v184, 10, v16
	global_load_dword v31, v[26:27], off
	v_lshlrev_b64 v[26:27], 13, v[184:185]
	v_lshl_add_u64 v[26:27], v[18:19], 0, v[26:27]
	v_or_b32_e32 v184, 12, v16
	global_load_dword v32, v[26:27], off
	v_lshlrev_b64 v[26:27], 13, v[184:185]
	v_lshl_add_u64 v[26:27], v[18:19], 0, v[26:27]
	v_or_b32_e32 v184, 14, v16
	global_load_dword v33, v[26:27], off
	v_lshlrev_b64 v[26:27], 13, v[184:185]
	v_lshl_add_u64 v[26:27], v[18:19], 0, v[26:27]
	v_or_b32_e32 v184, 16, v16
	global_load_dword v34, v[26:27], off
	s_waitcnt vmcnt(2)
	v_lshlrev_b64 v[26:27], 13, v[184:185]
	v_lshl_add_u64 v[26:27], v[18:19], 0, v[26:27]
	v_or_b32_e32 v184, 18, v16
	global_load_dword v35, v[26:27], off
	v_lshlrev_b64 v[26:27], 13, v[184:185]
	v_lshl_add_u64 v[26:27], v[18:19], 0, v[26:27]
	v_or_b32_e32 v184, 20, v16
	global_load_dword v36, v[26:27], off
	v_lshlrev_b64 v[26:27], 13, v[184:185]
	v_lshl_add_u64 v[26:27], v[18:19], 0, v[26:27]
	v_or_b32_e32 v184, 22, v16
	global_load_dword v37, v[26:27], off
	v_lshlrev_b64 v[26:27], 13, v[184:185]
	v_lshl_add_u64 v[26:27], v[18:19], 0, v[26:27]
	v_or_b32_e32 v184, 24, v16
	global_load_dword v38, v[26:27], off
	v_lshlrev_b64 v[26:27], 13, v[184:185]
	v_lshl_add_u64 v[26:27], v[18:19], 0, v[26:27]
	v_or_b32_e32 v184, 26, v16
	global_load_dword v39, v[26:27], off
	v_lshlrev_b64 v[26:27], 13, v[184:185]
	v_lshl_add_u64 v[26:27], v[18:19], 0, v[26:27]
	v_or_b32_e32 v184, 28, v16
	global_load_dword v40, v[26:27], off
	v_lshlrev_b64 v[26:27], 13, v[184:185]
	v_lshl_add_u64 v[26:27], v[18:19], 0, v[26:27]
	v_or_b32_e32 v184, 30, v16
	global_load_dword v41, v[26:27], off
	v_lshlrev_b64 v[26:27], 13, v[184:185]
	v_lshl_add_u64 v[26:27], v[18:19], 0, v[26:27]
	v_or_b32_e32 v184, 32, v16
	global_load_dword v42, v[26:27], off
	s_waitcnt vmcnt(2)
	v_lshlrev_b64 v[26:27], 13, v[184:185]
	v_lshl_add_u64 v[26:27], v[18:19], 0, v[26:27]
	v_or_b32_e32 v184, 34, v16
	global_load_dword v43, v[26:27], off
	v_lshlrev_b64 v[26:27], 13, v[184:185]
	v_lshl_add_u64 v[26:27], v[18:19], 0, v[26:27]
	v_or_b32_e32 v184, 36, v16
	global_load_dword v44, v[26:27], off
	v_lshlrev_b64 v[26:27], 13, v[184:185]
	v_lshl_add_u64 v[26:27], v[18:19], 0, v[26:27]
	v_or_b32_e32 v184, 38, v16
	global_load_dword v45, v[26:27], off
	v_lshlrev_b64 v[26:27], 13, v[184:185]
	v_lshl_add_u64 v[26:27], v[18:19], 0, v[26:27]
	v_or_b32_e32 v184, 40, v16
	global_load_dword v46, v[26:27], off
	v_lshlrev_b64 v[26:27], 13, v[184:185]
	v_lshl_add_u64 v[26:27], v[18:19], 0, v[26:27]
	v_or_b32_e32 v184, 42, v16
	global_load_dword v47, v[26:27], off
	v_lshlrev_b64 v[26:27], 13, v[184:185]
	v_lshl_add_u64 v[26:27], v[18:19], 0, v[26:27]
	v_or_b32_e32 v184, 44, v16
	global_load_dword v48, v[26:27], off
	v_lshlrev_b64 v[26:27], 13, v[184:185]
	v_lshl_add_u64 v[26:27], v[18:19], 0, v[26:27]
	v_or_b32_e32 v184, 46, v16
	global_load_dword v49, v[26:27], off
	v_lshlrev_b64 v[26:27], 13, v[184:185]
	v_lshl_add_u64 v[26:27], v[18:19], 0, v[26:27]
	v_or_b32_e32 v184, 48, v16
	global_load_dword v50, v[26:27], off
	s_waitcnt vmcnt(2)
; #define LAS __attribute__((address_space(3)))
; #define LDS_WAIT() asm volatile("s_waitcnt lgkmcnt(0)" ::: "memory")
; __device__ __forceinline__ unsigned pk2(float lo, float hi) { return cvt_pk_bf16(lo, hi); }
; __device__ __forceinline__ void transpose_item(const float* W, int ldw, int k0, int n0, bf16* WT, int Kdst, int dst_row0, LAS float* scr, int lane) {
;     ...
;     for (int i = 0; i < 32; ++i) { const int kk = 2 * i + (lane >> 5); scr[kk * 33 + (lane & 31)] = tv[i]; }
;     LDS_WAIT(); asm volatile("" ::: "memory");
;     const int c = lane & 7;
; #pragma unroll
;     for (int j = 0; j < 4; ++j) { const int n = (lane >> 3) + 8 * j; const LAS float* s = scr + (8 * c) * 33 + n;
;         v4u o; o.x = pk2(s[0 * 33], s[1 * 33]); o.y = pk2(s[2 * 33], s[3 * 33]); o.z = pk2(s[4 * 33], s[5 * 33]); o.w = pk2(s[6 * 33], s[7 * 33]);
;         *(v4u*)(WT + (size_t)(dst_row0 + n) * Kdst + k0 + 8 * c) = o; }
;     LDS_WAIT(); asm volatile("" ::: "memory");
	v_lshlrev_b64 v[26:27], 13, v[184:185]
	v_lshl_add_u64 v[26:27], v[18:19], 0, v[26:27]
	v_or_b32_e32 v184, 50, v16
	global_load_dword v51, v[26:27], off
	v_lshlrev_b64 v[26:27], 13, v[184:185]
	v_lshl_add_u64 v[26:27], v[18:19], 0, v[26:27]
	v_or_b32_e32 v184, 52, v16
	global_load_dword v52, v[26:27], off
	v_lshlrev_b64 v[26:27], 13, v[184:185]
	v_lshl_add_u64 v[26:27], v[18:19], 0, v[26:27]
	v_or_b32_e32 v184, 54, v16
	global_load_dword v53, v[26:27], off
	v_lshlrev_b64 v[26:27], 13, v[184:185]
	v_lshl_add_u64 v[26:27], v[18:19], 0, v[26:27]
	v_or_b32_e32 v184, 56, v16
	global_load_dword v54, v[26:27], off
	v_lshlrev_b64 v[26:27], 13, v[184:185]
	v_lshl_add_u64 v[26:27], v[18:19], 0, v[26:27]
	v_or_b32_e32 v184, 58, v16
	global_load_dword v55, v[26:27], off
	v_lshlrev_b64 v[26:27], 13, v[184:185]
	v_lshl_add_u64 v[26:27], v[18:19], 0, v[26:27]
	v_or_b32_e32 v184, 60, v16
	global_load_dword v56, v[26:27], off
	v_lshlrev_b64 v[26:27], 13, v[184:185]
	v_or_b32_e32 v184, 62, v16
	v_lshlrev_b64 v[16:17], 13, v[184:185]
	v_lshl_add_u64 v[26:27], v[18:19], 0, v[26:27]
	v_lshl_add_u64 v[16:17], v[18:19], 0, v[16:17]
	global_load_dword v26, v[26:27], off
	s_nop 0
	global_load_dword v16, v[16:17], off
	s_waitcnt vmcnt(30)
	ds_write2_b32 v20, v15, v28 offset1:66
	s_waitcnt vmcnt(28)
	ds_write2_b32 v20, v29, v30 offset0:132 offset1:198
	v_add_u32_e32 v15, 0x400, v20
	s_waitcnt vmcnt(26)
	ds_write2_b32 v15, v31, v32 offset0:8 offset1:74
	s_waitcnt vmcnt(24)
	ds_write2_b32 v15, v33, v34 offset0:140 offset1:206
	v_add_u32_e32 v15, 0x800, v20
	s_waitcnt vmcnt(22)
	ds_write2_b32 v15, v35, v36 offset0:16 offset1:82
	s_waitcnt vmcnt(20)
	ds_write2_b32 v15, v37, v38 offset0:148 offset1:214
	v_add_u32_e32 v15, 0xc00, v20
	s_waitcnt vmcnt(18)
	ds_write2_b32 v15, v39, v40 offset0:24 offset1:90
	s_waitcnt vmcnt(16)
	ds_write2_b32 v15, v41, v42 offset0:156 offset1:222
	v_add_u32_e32 v15, 0x1000, v20
	s_waitcnt vmcnt(14)
	ds_write2_b32 v15, v43, v44 offset0:32 offset1:98
	s_waitcnt vmcnt(12)
	ds_write2_b32 v15, v45, v46 offset0:164 offset1:230
	v_add_u32_e32 v15, 0x1400, v20
	s_waitcnt vmcnt(10)
	ds_write2_b32 v15, v47, v48 offset0:40 offset1:106
	s_waitcnt vmcnt(8)
	ds_write2_b32 v15, v49, v50 offset0:172 offset1:238
	v_add_u32_e32 v15, 0x1800, v20
	s_waitcnt vmcnt(6)
	ds_write2_b32 v15, v51, v52 offset0:48 offset1:114
	s_waitcnt vmcnt(4)
	ds_write2_b32 v15, v53, v54 offset0:180 offset1:246
	v_add_u32_e32 v15, 0x1c00, v20
	s_waitcnt vmcnt(2)
	ds_write2_b32 v15, v55, v56 offset0:56 offset1:122
	s_waitcnt vmcnt(0)
	ds_write2_b32 v15, v26, v16 offset0:188 offset1:254
	s_waitcnt lgkmcnt(0)
	ds_read2_b32 v[28:29], v22 offset0:33 offset1:41
	ds_read2_b32 v[30:31], v22 offset1:8
	ds_read2_b32 v[32:33], v22 offset0:66 offset1:74
	ds_read2_b32 v[34:35], v22 offset0:99 offset1:107
	ds_read2_b32 v[36:37], v22 offset0:132 offset1:140
	ds_read2_b32 v[38:39], v22 offset0:165 offset1:173
	ds_read2_b32 v[40:41], v22 offset0:198 offset1:206
	ds_read2_b32 v[42:43], v22 offset0:231 offset1:239
	v_or_b32_e32 v15, s16, v21
	v_lshl_add_u64 v[26:27], s[82:83], 1, v[6:7]
	v_lshlrev_b32_e32 v184, 11, v15
	v_or_b32_e32 v15, s16, v23
	s_waitcnt lgkmcnt(6)
	v_cvt_pk_bf16_f32 v16, v30, v28
	s_waitcnt lgkmcnt(4)
	v_cvt_pk_bf16_f32 v17, v32, v34
	s_waitcnt lgkmcnt(2)
	v_cvt_pk_bf16_f32 v18, v36, v38
	s_waitcnt lgkmcnt(0)
	v_cvt_pk_bf16_f32 v19, v40, v42
	v_lshl_add_u64 v[44:45], v[26:27], 0, v[184:185]
	v_lshlrev_b32_e32 v184, 11, v15
	global_store_dwordx4 v[44:45], v[16:19], off
	v_or_b32_e32 v15, s16, v24
	s_nop 0
	v_cvt_pk_bf16_f32 v16, v31, v29
	v_cvt_pk_bf16_f32 v17, v33, v35
	v_cvt_pk_bf16_f32 v18, v37, v39
	v_cvt_pk_bf16_f32 v19, v41, v43
	v_lshl_add_u64 v[28:29], v[26:27], 0, v[184:185]
	global_store_dwordx4 v[28:29], v[16:19], off
	ds_read2_b32 v[28:29], v22 offset0:49 offset1:57
	ds_read2_b32 v[30:31], v22 offset0:16 offset1:24
	ds_read2_b32 v[32:33], v22 offset0:82 offset1:90
	ds_read2_b32 v[34:35], v22 offset0:115 offset1:123
	ds_read2_b32 v[36:37], v22 offset0:148 offset1:156
	ds_read2_b32 v[38:39], v22 offset0:181 offset1:189
	ds_read2_b32 v[40:41], v22 offset0:214 offset1:222
	ds_read2_b32 v[42:43], v22 offset0:247 offset1:255
	v_lshlrev_b32_e32 v184, 11, v15
	v_or_b32_e32 v15, s16, v25
	s_waitcnt lgkmcnt(6)
	v_cvt_pk_bf16_f32 v16, v30, v28
	s_waitcnt lgkmcnt(4)
	v_cvt_pk_bf16_f32 v17, v32, v34
	s_waitcnt lgkmcnt(2)
	v_cvt_pk_bf16_f32 v18, v36, v38
	s_waitcnt lgkmcnt(0)
	v_cvt_pk_bf16_f32 v19, v40, v42
	v_lshl_add_u64 v[44:45], v[26:27], 0, v[184:185]
	v_lshlrev_b32_e32 v184, 11, v15
	global_store_dwordx4 v[44:45], v[16:19], off
	v_lshl_add_u64 v[26:27], v[26:27], 0, v[184:185]
	s_nop 0
	v_cvt_pk_bf16_f32 v16, v31, v29
	v_cvt_pk_bf16_f32 v17, v33, v35
	v_cvt_pk_bf16_f32 v18, v37, v39
	v_cvt_pk_bf16_f32 v19, v41, v43
	global_store_dwordx4 v[26:27], v[16:19], off
	s_waitcnt lgkmcnt(0)

; #define LAS __attribute__((address_space(3)))
; __device__ __forceinline__ void transpose_item(const float* W, int ldw, int k0, int n0, bf16* WT, int Kdst, int dst_row0, LAS float* scr, int lane) {
;     float tv[32];
; #pragma unroll
;     for (int i = 0; i < 32; ++i) { const int kk = 2 * i + (lane >> 5); tv[i] = W[(size_t)(k0 + kk) * ldw + n0 + (lane & 31)]; }
; __device__ __forceinline__ void phase_wconv(const Frame& F, const Args& a, int l, unsigned char* wt, unsigned char* wth, int part) {
;     ...
;         if (r < I_BA) { const int kb = r / 64, nb = r % 64; transpose_item(a.in[F.z + 21] + (size_t)l * 512 * D, D, 64 * kb, 32 * nb, (bf16*)(wth + WO_BA), 512, 32 * nb, scr, F.lane); continue; }
.LBB0_715:
	s_andn2_b64 vcc, exec, s[16:17]
	s_cbranch_vccnz .LBB0_717
	s_and_b32 s16, s30, 0xffc0
	s_add_i32 s82, s16, 0xffff3e80
	s_load_dwordx2 s[16:17], s[14:15], 0xa8
	v_readlane_b32 s18, v254, 36
	v_readlane_b32 s19, v254, 37
	s_lshl_b64 s[18:19], s[18:19], 2
	v_or_b32_e32 v16, s82, v1
	s_waitcnt lgkmcnt(0)
	s_add_u32 s18, s16, s18
	s_addc_u32 s17, s17, s19
	s_and_b32 s16, s28, 0x7e0
	s_lshl_b32 s19, s16, 2
	s_add_u32 s18, s18, s19
	s_addc_u32 s19, s17, 0
	v_lshlrev_b32_e32 v184, 2, v0
	v_mov_b32_e32 v17, v185
	v_lshl_add_u64 v[18:19], s[18:19], 0, v[184:185]
	v_lshlrev_b64 v[26:27], 13, v[16:17]
	v_lshl_add_u64 v[26:27], v[18:19], 0, v[26:27]
	v_or_b32_e32 v184, 2, v16
	global_load_dword v15, v[26:27], off
	v_lshlrev_b64 v[26:27], 13, v[184:185]
	v_lshl_add_u64 v[26:27], v[18:19], 0, v[26:27]
	v_or_b32_e32 v184, 4, v16
	global_load_dword v28, v[26:27], off
	v_lshlrev_b64 v[26:27], 13, v[184:185]
	v_lshl_add_u64 v[26:27], v[18:19], 0, v[26:27]
	v_or_b32_e32 v184, 6, v16
	global_load_dword v29, v[26:27], off
	v_lshlrev_b64 v[26:27], 13, v[184:185]
	v_lshl_add_u64 v[26:27], v[18:19], 0, v[26:27]
	v_or_b32_e32 v184, 8, v16
	global_load_dword v30, v[26:27], off
	v_lshlrev_b64 v[26:27], 13, v[184:185]
	v_lshl_add_u64 v[26:27], v[18:19], 0, v[26:27]
	v_or_b32_e32 v184, 10, v16
	global_load_dword v31, v[26:27], off
	v_lshlrev_b64 v[26:27], 13, v[184:185]
	v_lshl_add_u64 v[26:27], v[18:19], 0, v[26:27]
	v_or_b32_e32 v184, 12, v16
	global_load_dword v32, v[26:27], off
	v_lshlrev_b64 v[26:27], 13, v[184:185]
	v_lshl_add_u64 v[26:27], v[18:19], 0, v[26:27]
	v_or_b32_e32 v184, 14, v16
	global_load_dword v33, v[26:27], off
	v_lshlrev_b64 v[26:27], 13, v[184:185]
	v_lshl_add_u64 v[26:27], v[18:19], 0, v[26:27]
	v_or_b32_e32 v184, 16, v16
	global_load_dword v34, v[26:27], off
	s_waitcnt vmcnt(2)
	v_lshlrev_b64 v[26:27], 13, v[184:185]
	v_lshl_add_u64 v[26:27], v[18:19], 0, v[26:27]
	v_or_b32_e32 v184, 18, v16
	global_load_dword v35, v[26:27], off
	v_lshlrev_b64 v[26:27], 13, v[184:185]
	v_lshl_add_u64 v[26:27], v[18:19], 0, v[26:27]
	v_or_b32_e32 v184, 20, v16
	global_load_dword v36, v[26:27], off
	v_lshlrev_b64 v[26:27], 13, v[184:185]
	v_lshl_add_u64 v[26:27], v[18:19], 0, v[26:27]
	v_or_b32_e32 v184, 22, v16
	global_load_dword v37, v[26:27], off
	v_lshlrev_b64 v[26:27], 13, v[184:185]
	v_lshl_add_u64 v[26:27], v[18:19], 0, v[26:27]
	v_or_b32_e32 v184, 24, v16
	global_load_dword v38, v[26:27], off
	v_lshlrev_b64 v[26:27], 13, v[184:185]
	v_lshl_add_u64 v[26:27], v[18:19], 0, v[26:27]
	v_or_b32_e32 v184, 26, v16
	global_load_dword v39, v[26:27], off
	v_lshlrev_b64 v[26:27], 13, v[184:185]
	v_lshl_add_u64 v[26:27], v[18:19], 0, v[26:27]
	v_or_b32_e32 v184, 28, v16
	global_load_dword v40, v[26:27], off
	v_lshlrev_b64 v[26:27], 13, v[184:185]
	v_lshl_add_u64 v[26:27], v[18:19], 0, v[26:27]
	v_or_b32_e32 v184, 30, v16
	global_load_dword v41, v[26:27], off
	v_lshlrev_b64 v[26:27], 13, v[184:185]
	v_lshl_add_u64 v[26:27], v[18:19], 0, v[26:27]
	v_or_b32_e32 v184, 32, v16
	global_load_dword v42, v[26:27], off
	s_waitcnt vmcnt(2)
	v_lshlrev_b64 v[26:27], 13, v[184:185]
	v_lshl_add_u64 v[26:27], v[18:19], 0, v[26:27]
	v_or_b32_e32 v184, 34, v16
	global_load_dword v43, v[26:27], off
	v_lshlrev_b64 v[26:27], 13, v[184:185]
	v_lshl_add_u64 v[26:27], v[18:19], 0, v[26:27]
	v_or_b32_e32 v184, 36, v16
	global_load_dword v44, v[26:27], off
	v_lshlrev_b64 v[26:27], 13, v[184:185]
	v_lshl_add_u64 v[26:27], v[18:19], 0, v[26:27]
	v_or_b32_e32 v184, 38, v16
	global_load_dword v45, v[26:27], off
	v_lshlrev_b64 v[26:27], 13, v[184:185]
	v_lshl_add_u64 v[26:27], v[18:19], 0, v[26:27]
	v_or_b32_e32 v184, 40, v16
	global_load_dword v46, v[26:27], off
	v_lshlrev_b64 v[26:27], 13, v[184:185]
	v_lshl_add_u64 v[26:27], v[18:19], 0, v[26:27]
	v_or_b32_e32 v184, 42, v16
	global_load_dword v47, v[26:27], off
	v_lshlrev_b64 v[26:27], 13, v[184:185]
	v_lshl_add_u64 v[26:27], v[18:19], 0, v[26:27]
	v_or_b32_e32 v184, 44, v16
	global_load_dword v48, v[26:27], off
	v_lshlrev_b64 v[26:27], 13, v[184:185]
	v_lshl_add_u64 v[26:27], v[18:19], 0, v[26:27]
	v_or_b32_e32 v184, 46, v16
	global_load_dword v49, v[26:27], off
	v_lshlrev_b64 v[26:27], 13, v[184:185]
	v_lshl_add_u64 v[26:27], v[18:19], 0, v[26:27]
	v_or_b32_e32 v184, 48, v16
	global_load_dword v50, v[26:27], off
	s_waitcnt vmcnt(2)
; #define LAS __attribute__((address_space(3)))
; #define LDS_WAIT() asm volatile("s_waitcnt lgkmcnt(0)" ::: "memory")
; __device__ __forceinline__ unsigned pk2(float lo, float hi) { return cvt_pk_bf16(lo, hi); }
; __device__ __forceinline__ void transpose_item(const float* W, int ldw, int k0, int n0, bf16* WT, int Kdst, int dst_row0, LAS float* scr, int lane) {
;     ...
;     for (int i = 0; i < 32; ++i) { const int kk = 2 * i + (lane >> 5); scr[kk * 33 + (lane & 31)] = tv[i]; }
;     LDS_WAIT(); asm volatile("" ::: "memory");
;     const int c = lane & 7;
; #pragma unroll
;     for (int j = 0; j < 4; ++j) { const int n = (lane >> 3) + 8 * j; const LAS float* s = scr + (8 * c) * 33 + n;
;         v4u o; o.x = pk2(s[0 * 33], s[1 * 33]); o.y = pk2(s[2 * 33], s[3 * 33]); o.z = pk2(s[4 * 33], s[5 * 33]); o.w = pk2(s[6 * 33], s[7 * 33]);
;         *(v4u*)(WT + (size_t)(dst_row0 + n) * Kdst + k0 + 8 * c) = o; }
;     LDS_WAIT(); asm volatile("" ::: "memory");
	v_lshlrev_b64 v[26:27], 13, v[184:185]
	v_lshl_add_u64 v[26:27], v[18:19], 0, v[26:27]
	v_or_b32_e32 v184, 50, v16
	global_load_dword v51, v[26:27], off
	v_lshlrev_b64 v[26:27], 13, v[184:185]
	v_lshl_add_u64 v[26:27], v[18:19], 0, v[26:27]
	v_or_b32_e32 v184, 52, v16
	global_load_dword v52, v[26:27], off
	v_lshlrev_b64 v[26:27], 13, v[184:185]
	v_lshl_add_u64 v[26:27], v[18:19], 0, v[26:27]
	v_or_b32_e32 v184, 54, v16
	global_load_dword v53, v[26:27], off
	v_lshlrev_b64 v[26:27], 13, v[184:185]
	v_lshl_add_u64 v[26:27], v[18:19], 0, v[26:27]
	v_or_b32_e32 v184, 56, v16
	global_load_dword v54, v[26:27], off
	v_lshlrev_b64 v[26:27], 13, v[184:185]
	v_lshl_add_u64 v[26:27], v[18:19], 0, v[26:27]
	v_or_b32_e32 v184, 58, v16
	global_load_dword v55, v[26:27], off
	v_lshlrev_b64 v[26:27], 13, v[184:185]
	v_lshl_add_u64 v[26:27], v[18:19], 0, v[26:27]
	v_or_b32_e32 v184, 60, v16
	global_load_dword v56, v[26:27], off
	v_lshlrev_b64 v[26:27], 13, v[184:185]
	v_or_b32_e32 v184, 62, v16
	v_lshlrev_b64 v[16:17], 13, v[184:185]
	v_lshl_add_u64 v[26:27], v[18:19], 0, v[26:27]
	v_lshl_add_u64 v[16:17], v[18:19], 0, v[16:17]
	global_load_dword v26, v[26:27], off
	s_nop 0
	global_load_dword v16, v[16:17], off
	s_waitcnt vmcnt(30)
	ds_write2_b32 v20, v15, v28 offset1:66
	s_waitcnt vmcnt(28)
	ds_write2_b32 v20, v29, v30 offset0:132 offset1:198
	v_add_u32_e32 v15, 0x400, v20
	s_waitcnt vmcnt(26)
	ds_write2_b32 v15, v31, v32 offset0:8 offset1:74
	s_waitcnt vmcnt(24)
	ds_write2_b32 v15, v33, v34 offset0:140 offset1:206
	v_add_u32_e32 v15, 0x800, v20
	s_waitcnt vmcnt(22)
	ds_write2_b32 v15, v35, v36 offset0:16 offset1:82
	s_waitcnt vmcnt(20)
	ds_write2_b32 v15, v37, v38 offset0:148 offset1:214
	v_add_u32_e32 v15, 0xc00, v20
	s_waitcnt vmcnt(18)
	ds_write2_b32 v15, v39, v40 offset0:24 offset1:90
	s_waitcnt vmcnt(16)
	ds_write2_b32 v15, v41, v42 offset0:156 offset1:222
	v_add_u32_e32 v15, 0x1000, v20
	s_waitcnt vmcnt(14)
	ds_write2_b32 v15, v43, v44 offset0:32 offset1:98
	s_waitcnt vmcnt(12)
	ds_write2_b32 v15, v45, v46 offset0:164 offset1:230
	v_add_u32_e32 v15, 0x1400, v20
	s_waitcnt vmcnt(10)
	ds_write2_b32 v15, v47, v48 offset0:40 offset1:106
	s_waitcnt vmcnt(8)
	ds_write2_b32 v15, v49, v50 offset0:172 offset1:238
	v_add_u32_e32 v15, 0x1800, v20
	s_waitcnt vmcnt(6)
	ds_write2_b32 v15, v51, v52 offset0:48 offset1:114
	s_waitcnt vmcnt(4)
	ds_write2_b32 v15, v53, v54 offset0:180 offset1:246
	v_add_u32_e32 v15, 0x1c00, v20
	s_waitcnt vmcnt(2)
	ds_write2_b32 v15, v55, v56 offset0:56 offset1:122
	s_waitcnt vmcnt(0)
	ds_write2_b32 v15, v26, v16 offset0:188 offset1:254
	s_waitcnt lgkmcnt(0)
	ds_read2_b32 v[28:29], v22 offset0:33 offset1:41
	ds_read2_b32 v[30:31], v22 offset1:8
	ds_read2_b32 v[32:33], v22 offset0:66 offset1:74
	ds_read2_b32 v[34:35], v22 offset0:99 offset1:107
	ds_read2_b32 v[36:37], v22 offset0:132 offset1:140
	ds_read2_b32 v[38:39], v22 offset0:165 offset1:173
	ds_read2_b32 v[40:41], v22 offset0:198 offset1:206
	ds_read2_b32 v[42:43], v22 offset0:231 offset1:239
	v_or_b32_e32 v15, s16, v21
	v_lshl_add_u64 v[26:27], s[82:83], 1, v[8:9]
	v_lshlrev_b32_e32 v184, 10, v15
	v_or_b32_e32 v15, s16, v23
	s_waitcnt lgkmcnt(6)
	v_cvt_pk_bf16_f32 v16, v30, v28
	s_waitcnt lgkmcnt(4)
	v_cvt_pk_bf16_f32 v17, v32, v34
	s_waitcnt lgkmcnt(2)
	v_cvt_pk_bf16_f32 v18, v36, v38
	s_waitcnt lgkmcnt(0)
	v_cvt_pk_bf16_f32 v19, v40, v42
	v_lshl_add_u64 v[44:45], v[26:27], 0, v[184:185]
	v_lshlrev_b32_e32 v184, 10, v15
	global_store_dwordx4 v[44:45], v[16:19], off
	v_or_b32_e32 v15, s16, v24
	s_nop 0
	v_cvt_pk_bf16_f32 v16, v31, v29
	v_cvt_pk_bf16_f32 v17, v33, v35
	v_cvt_pk_bf16_f32 v18, v37, v39
	v_cvt_pk_bf16_f32 v19, v41, v43
	v_lshl_add_u64 v[28:29], v[26:27], 0, v[184:185]
	global_store_dwordx4 v[28:29], v[16:19], off
	ds_read2_b32 v[28:29], v22 offset0:49 offset1:57
	ds_read2_b32 v[30:31], v22 offset0:16 offset1:24
	ds_read2_b32 v[32:33], v22 offset0:82 offset1:90
	ds_read2_b32 v[34:35], v22 offset0:115 offset1:123
	ds_read2_b32 v[36:37], v22 offset0:148 offset1:156
	ds_read2_b32 v[38:39], v22 offset0:181 offset1:189
	ds_read2_b32 v[40:41], v22 offset0:214 offset1:222
	ds_read2_b32 v[42:43], v22 offset0:247 offset1:255
	v_lshlrev_b32_e32 v184, 10, v15
	v_or_b32_e32 v15, s16, v25
	s_waitcnt lgkmcnt(6)
	v_cvt_pk_bf16_f32 v16, v30, v28
	s_waitcnt lgkmcnt(4)
	v_cvt_pk_bf16_f32 v17, v32, v34
	s_waitcnt lgkmcnt(2)
	v_cvt_pk_bf16_f32 v18, v36, v38
	s_waitcnt lgkmcnt(0)
	v_cvt_pk_bf16_f32 v19, v40, v42
	v_lshl_add_u64 v[44:45], v[26:27], 0, v[184:185]
	v_lshlrev_b32_e32 v184, 10, v15
	global_store_dwordx4 v[44:45], v[16:19], off
	v_lshl_add_u64 v[26:27], v[26:27], 0, v[184:185]
	s_nop 0
	v_cvt_pk_bf16_f32 v16, v31, v29
	v_cvt_pk_bf16_f32 v17, v33, v35
	v_cvt_pk_bf16_f32 v18, v37, v39
	v_cvt_pk_bf16_f32 v19, v41, v43
	global_store_dwordx4 v[26:27], v[16:19], off
	s_waitcnt lgkmcnt(0)

; __device__ __forceinline__ void transpose_item(const float* W, int ldw, int k0, int n0, bf16* WT, int Kdst, int dst_row0, LAS float* scr, int lane) {
;     ...
;     for (int i = 0; i < 32; ++i) { const int kk = 2 * i + (lane >> 5); tv[i] = W[(size_t)(k0 + kk) * ldw + n0 + (lane & 31)]; }
; __device__ __forceinline__ void phase_wconv(const Frame& F, const Args& a, int l, unsigned char* wt, unsigned char* wth, int part) {
;     ...
;         if (r < I_IN) {
;             const float* W = a.in[F.z + 7] + (size_t)l * D * 15744;
;             const int kb = r / 492, nb = r % 492, n0 = 32 * nb;
;             if (!(((n0 >= 7680 && n0 < 9600) ? 1 : 2) & part)) continue;
;             bf16* dst; int row;
;             if (n0 < 4608) { dst = (bf16*)(wth + WO_ATT); row = n0; }
;             else if (n0 < 7680) { dst = (bf16*)(wth + WO_RET); row = n0 - 4608; }
;             else if (n0 < 9600) { dst = (bf16*)(wth + WO_CF); row = n0 - 7680; }
;             else { dst = (bf16*)(wth + WO_GATE); row = n0 - 9600; }
;             transpose_item(W, 15744, 64 * kb, n0, dst, D, row, scr, F.lane);
.LBB0_729:
	v_readlane_b32 s20, v254, 52
	v_readlane_b32 s21, v254, 53
	s_waitcnt lgkmcnt(0)
	s_add_u32 s20, s18, s20
	s_addc_u32 s19, s19, s21
	s_lshl_b32 s18, s34, 6
	s_and_b32 s18, s18, 0x3fc0
	s_lshl_b32 s21, s35, 2
	s_add_u32 s20, s20, s21
	v_or_b32_e32 v15, s18, v1
	s_addc_u32 s21, s19, 0
	v_lshlrev_b32_e32 v184, 2, v0
	v_lshl_add_u64 v[16:17], s[20:21], 0, v[184:185]
	v_mul_u32_u24_e32 v184, 0xf600, v15
	v_lshl_add_u64 v[16:17], v[16:17], 0, v[184:185]
	s_mov_b32 s19, 0x1e000
	v_add_co_u32_e32 v18, vcc, s19, v16
	s_mov_b32 s19, 0x3d000
	s_nop 0
	v_addc_co_u32_e32 v19, vcc, 0, v17, vcc
	global_load_dword v26, v[18:19], off offset:3072
	v_add_co_u32_e32 v18, vcc, s19, v16
	s_mov_b32 s19, 0x5c000
	s_nop 0
	v_addc_co_u32_e32 v19, vcc, 0, v17, vcc
	global_load_dword v27, v[18:19], off offset:2048
	v_add_co_u32_e32 v18, vcc, s19, v16
	s_mov_b32 s19, 0x7b000
	s_nop 0
	v_addc_co_u32_e32 v19, vcc, 0, v17, vcc
	global_load_dword v28, v[18:19], off offset:1024
	v_add_co_u32_e32 v18, vcc, s19, v16
	s_mov_b32 s19, 0x99000
	s_nop 0
	v_addc_co_u32_e32 v19, vcc, 0, v17, vcc
	global_load_dword v15, v[16:17], off
	global_load_dword v29, v[18:19], off
	v_add_co_u32_e32 v18, vcc, s19, v16
	s_mov_b32 s19, 0xb8000
	s_nop 0
	v_addc_co_u32_e32 v19, vcc, 0, v17, vcc
	global_load_dword v30, v[18:19], off offset:3072
	v_add_co_u32_e32 v18, vcc, s19, v16
	s_mov_b32 s19, 0xd7000
	s_nop 0
	v_addc_co_u32_e32 v19, vcc, 0, v17, vcc
	global_load_dword v31, v[18:19], off offset:2048
	v_add_co_u32_e32 v18, vcc, s19, v16
	s_mov_b32 s19, 0xf6000
	s_nop 0
	v_addc_co_u32_e32 v19, vcc, 0, v17, vcc
	global_load_dword v32, v[18:19], off offset:1024
	s_waitcnt vmcnt(2)
	v_add_co_u32_e32 v18, vcc, s19, v16
	s_mov_b32 s19, 0x114000
	s_nop 0
	v_addc_co_u32_e32 v19, vcc, 0, v17, vcc
	global_load_dword v33, v[18:19], off
	v_add_co_u32_e32 v18, vcc, s19, v16
	s_mov_b32 s19, 0x133000
	s_nop 0
	v_addc_co_u32_e32 v19, vcc, 0, v17, vcc
	global_load_dword v34, v[18:19], off offset:3072
	v_add_co_u32_e32 v18, vcc, s19, v16
	s_mov_b32 s19, 0x152000
	s_nop 0
	v_addc_co_u32_e32 v19, vcc, 0, v17, vcc
	global_load_dword v35, v[18:19], off offset:2048
	v_add_co_u32_e32 v18, vcc, s19, v16
	s_mov_b32 s19, 0x171000
	s_nop 0
	v_addc_co_u32_e32 v19, vcc, 0, v17, vcc
	global_load_dword v36, v[18:19], off offset:1024
	v_add_co_u32_e32 v18, vcc, s19, v16
	s_mov_b32 s19, 0x18f000
	s_nop 0
	v_addc_co_u32_e32 v19, vcc, 0, v17, vcc
	global_load_dword v37, v[18:19], off
	v_add_co_u32_e32 v18, vcc, s19, v16
	s_mov_b32 s19, 0x1ae000
	s_nop 0
	v_addc_co_u32_e32 v19, vcc, 0, v17, vcc
	global_load_dword v38, v[18:19], off offset:3072
	v_add_co_u32_e32 v18, vcc, s19, v16
	s_mov_b32 s19, 0x1cd000
	s_nop 0
	v_addc_co_u32_e32 v19, vcc, 0, v17, vcc
	global_load_dword v39, v[18:19], off offset:2048
	v_add_co_u32_e32 v18, vcc, s19, v16
	s_mov_b32 s19, 0x1ec000
	s_nop 0
	v_addc_co_u32_e32 v19, vcc, 0, v17, vcc
	global_load_dword v40, v[18:19], off offset:1024
	s_waitcnt vmcnt(2)
	v_add_co_u32_e32 v18, vcc, s19, v16
	s_mov_b32 s19, 0x20a000
	s_nop 0
	v_addc_co_u32_e32 v19, vcc, 0, v17, vcc
	global_load_dword v41, v[18:19], off
	v_add_co_u32_e32 v18, vcc, s19, v16
	s_mov_b32 s19, 0x229000
	s_nop 0
	v_addc_co_u32_e32 v19, vcc, 0, v17, vcc
	global_load_dword v42, v[18:19], off offset:3072
	v_add_co_u32_e32 v18, vcc, s19, v16
	s_mov_b32 s19, 0x248000
	s_nop 0
	v_addc_co_u32_e32 v19, vcc, 0, v17, vcc
	global_load_dword v43, v[18:19], off offset:2048
	v_add_co_u32_e32 v18, vcc, s19, v16
	s_mov_b32 s19, 0x267000
	s_nop 0
	v_addc_co_u32_e32 v19, vcc, 0, v17, vcc
	global_load_dword v44, v[18:19], off offset:1024
	v_add_co_u32_e32 v18, vcc, s19, v16
	s_mov_b32 s19, 0x285000
	s_nop 0
	v_addc_co_u32_e32 v19, vcc, 0, v17, vcc
	global_load_dword v45, v[18:19], off
	v_add_co_u32_e32 v18, vcc, s19, v16
	s_mov_b32 s19, 0x2a4000
	s_nop 0
	v_addc_co_u32_e32 v19, vcc, 0, v17, vcc
	global_load_dword v46, v[18:19], off offset:3072
	v_add_co_u32_e32 v18, vcc, s19, v16
	s_mov_b32 s19, 0x2c3000
	s_nop 0
	v_addc_co_u32_e32 v19, vcc, 0, v17, vcc
	global_load_dword v47, v[18:19], off offset:2048
	v_add_co_u32_e32 v18, vcc, s19, v16
	s_mov_b32 s19, 0x2e2000
	s_nop 0
	v_addc_co_u32_e32 v19, vcc, 0, v17, vcc
	global_load_dword v48, v[18:19], off offset:1024
	s_waitcnt vmcnt(2)
; #define LAS __attribute__((address_space(3)))
; #define LDS_WAIT() asm volatile("s_waitcnt lgkmcnt(0)" ::: "memory")
; __device__ __forceinline__ unsigned pk2(float lo, float hi) { return cvt_pk_bf16(lo, hi); }
; __device__ __forceinline__ void transpose_item(const float* W, int ldw, int k0, int n0, bf16* WT, int Kdst, int dst_row0, LAS float* scr, int lane) {
;     ...
;     for (int i = 0; i < 32; ++i) { const int kk = 2 * i + (lane >> 5); scr[kk * 33 + (lane & 31)] = tv[i]; }
;     LDS_WAIT(); asm volatile("" ::: "memory");
;     const int c = lane & 7;
; #pragma unroll
;     for (int j = 0; j < 4; ++j) { const int n = (lane >> 3) + 8 * j; const LAS float* s = scr + (8 * c) * 33 + n;
;         v4u o; o.x = pk2(s[0 * 33], s[1 * 33]); o.y = pk2(s[2 * 33], s[3 * 33]); o.z = pk2(s[4 * 33], s[5 * 33]); o.w = pk2(s[6 * 33], s[7 * 33]);
;         *(v4u*)(WT + (size_t)(dst_row0 + n) * Kdst + k0 + 8 * c) = o; }
;     LDS_WAIT(); asm volatile("" ::: "memory");
	v_add_co_u32_e32 v18, vcc, s19, v16
	s_mov_b32 s19, 0x300000
	s_nop 0
	v_addc_co_u32_e32 v19, vcc, 0, v17, vcc
	global_load_dword v49, v[18:19], off
	v_add_co_u32_e32 v18, vcc, s19, v16
	s_mov_b32 s19, 0x31f000
	s_nop 0
	v_addc_co_u32_e32 v19, vcc, 0, v17, vcc
	global_load_dword v50, v[18:19], off offset:3072
	v_add_co_u32_e32 v18, vcc, s19, v16
	s_mov_b32 s19, 0x33e000
	s_nop 0
	v_addc_co_u32_e32 v19, vcc, 0, v17, vcc
	global_load_dword v51, v[18:19], off offset:2048
	v_add_co_u32_e32 v18, vcc, s19, v16
	s_mov_b32 s19, 0x35d000
	s_nop 0
	v_addc_co_u32_e32 v19, vcc, 0, v17, vcc
	global_load_dword v52, v[18:19], off offset:1024
	v_add_co_u32_e32 v18, vcc, s19, v16
	s_mov_b32 s19, 0x37b000
	s_nop 0
	v_addc_co_u32_e32 v19, vcc, 0, v17, vcc
	global_load_dword v53, v[18:19], off
	v_add_co_u32_e32 v18, vcc, s19, v16
	s_mov_b32 s19, 0x39a000
	s_nop 0
	v_addc_co_u32_e32 v19, vcc, 0, v17, vcc
	global_load_dword v54, v[18:19], off offset:3072
	v_add_co_u32_e32 v18, vcc, s19, v16
	s_mov_b32 s19, 0x3b9000
	s_nop 0
	v_addc_co_u32_e32 v19, vcc, 0, v17, vcc
	v_add_co_u32_e32 v16, vcc, s19, v16
	global_load_dword v18, v[18:19], off offset:2048
	s_nop 0
	v_addc_co_u32_e32 v17, vcc, 0, v17, vcc
	global_load_dword v16, v[16:17], off offset:1024
	s_waitcnt vmcnt(28)
	ds_write2_b32 v20, v15, v26 offset1:66
	ds_write2_b32 v20, v27, v28 offset0:132 offset1:198
	v_add_u32_e32 v15, 0x400, v20
	s_waitcnt vmcnt(26)
	ds_write2_b32 v15, v29, v30 offset0:8 offset1:74
	s_waitcnt vmcnt(24)
	ds_write2_b32 v15, v31, v32 offset0:140 offset1:206
	v_add_u32_e32 v15, 0x800, v20
	s_waitcnt vmcnt(22)
	ds_write2_b32 v15, v33, v34 offset0:16 offset1:82
	s_waitcnt vmcnt(20)
	ds_write2_b32 v15, v35, v36 offset0:148 offset1:214
	v_add_u32_e32 v15, 0xc00, v20
	s_waitcnt vmcnt(18)
	ds_write2_b32 v15, v37, v38 offset0:24 offset1:90
	s_waitcnt vmcnt(16)
	ds_write2_b32 v15, v39, v40 offset0:156 offset1:222
	v_add_u32_e32 v15, 0x1000, v20
	s_waitcnt vmcnt(14)
	ds_write2_b32 v15, v41, v42 offset0:32 offset1:98
	s_waitcnt vmcnt(12)
	ds_write2_b32 v15, v43, v44 offset0:164 offset1:230
	v_add_u32_e32 v15, 0x1400, v20
	s_waitcnt vmcnt(10)
	ds_write2_b32 v15, v45, v46 offset0:40 offset1:106
	s_waitcnt vmcnt(8)
	ds_write2_b32 v15, v47, v48 offset0:172 offset1:238
	v_add_u32_e32 v15, 0x1800, v20
	s_waitcnt vmcnt(6)
	ds_write2_b32 v15, v49, v50 offset0:48 offset1:114
	s_waitcnt vmcnt(4)
	ds_write2_b32 v15, v51, v52 offset0:180 offset1:246
	v_add_u32_e32 v15, 0x1c00, v20
	s_waitcnt vmcnt(2)
	ds_write2_b32 v15, v53, v54 offset0:56 offset1:122
	s_waitcnt vmcnt(0)
	ds_write2_b32 v15, v18, v16 offset0:188 offset1:254
	s_waitcnt lgkmcnt(0)
	ds_read2_b32 v[28:29], v22 offset0:33 offset1:41
	ds_read2_b32 v[30:31], v22 offset1:8
	ds_read2_b32 v[32:33], v22 offset0:66 offset1:74
	ds_read2_b32 v[34:35], v22 offset0:99 offset1:107
	ds_read2_b32 v[36:37], v22 offset0:132 offset1:140
	ds_read2_b32 v[38:39], v22 offset0:165 offset1:173
	ds_read2_b32 v[40:41], v22 offset0:198 offset1:206
	ds_read2_b32 v[42:43], v22 offset0:231 offset1:239
	s_lshl_b32 s18, s18, 1
	s_add_u32 s16, s16, s18
	v_add_u32_e32 v44, s31, v21
	s_addc_u32 s17, s17, 0
	v_mov_b32_e32 v15, v185
	v_ashrrev_i32_e32 v45, 31, v44
	v_lshl_add_u64 v[26:27], s[16:17], 0, v[14:15]
	v_lshlrev_b64 v[44:45], 12, v[44:45]
	s_waitcnt lgkmcnt(6)
	v_cvt_pk_bf16_f32 v16, v30, v28
	s_waitcnt lgkmcnt(4)
	v_cvt_pk_bf16_f32 v17, v32, v34
	s_waitcnt lgkmcnt(2)
	v_cvt_pk_bf16_f32 v18, v36, v38
	s_waitcnt lgkmcnt(0)
	v_cvt_pk_bf16_f32 v19, v40, v42
	v_lshl_add_u64 v[44:45], v[26:27], 0, v[44:45]
	v_add_u32_e32 v28, s31, v23
	global_store_dwordx4 v[44:45], v[16:19], off
	v_add_u32_e32 v44, s31, v24
	v_ashrrev_i32_e32 v45, 31, v44
	v_cvt_pk_bf16_f32 v16, v31, v29
	v_ashrrev_i32_e32 v29, 31, v28
	v_lshlrev_b64 v[28:29], 12, v[28:29]
	v_cvt_pk_bf16_f32 v17, v33, v35
	v_cvt_pk_bf16_f32 v18, v37, v39
	v_cvt_pk_bf16_f32 v19, v41, v43
	v_lshl_add_u64 v[28:29], v[26:27], 0, v[28:29]
	global_store_dwordx4 v[28:29], v[16:19], off
	ds_read2_b32 v[28:29], v22 offset0:49 offset1:57
	ds_read2_b32 v[30:31], v22 offset0:16 offset1:24
	ds_read2_b32 v[32:33], v22 offset0:82 offset1:90
	ds_read2_b32 v[34:35], v22 offset0:115 offset1:123
	ds_read2_b32 v[36:37], v22 offset0:148 offset1:156
	ds_read2_b32 v[38:39], v22 offset0:181 offset1:189
	ds_read2_b32 v[40:41], v22 offset0:214 offset1:222
	ds_read2_b32 v[42:43], v22 offset0:247 offset1:255
	v_lshlrev_b64 v[44:45], 12, v[44:45]
	s_waitcnt lgkmcnt(6)
	v_cvt_pk_bf16_f32 v16, v30, v28
	s_waitcnt lgkmcnt(4)
	v_cvt_pk_bf16_f32 v17, v32, v34
	s_waitcnt lgkmcnt(2)
	v_cvt_pk_bf16_f32 v18, v36, v38
	s_waitcnt lgkmcnt(0)
	v_cvt_pk_bf16_f32 v19, v40, v42
	v_lshl_add_u64 v[44:45], v[26:27], 0, v[44:45]
	v_add_u32_e32 v28, s31, v25
	global_store_dwordx4 v[44:45], v[16:19], off
	s_nop 1
	v_cvt_pk_bf16_f32 v16, v31, v29
	v_ashrrev_i32_e32 v29, 31, v28
	v_lshlrev_b64 v[28:29], 12, v[28:29]
	v_cvt_pk_bf16_f32 v17, v33, v35
	v_cvt_pk_bf16_f32 v18, v37, v39
	v_cvt_pk_bf16_f32 v19, v41, v43
	v_lshl_add_u64 v[26:27], v[26:27], 0, v[28:29]
	global_store_dwordx4 v[26:27], v[16:19], off
	s_waitcnt lgkmcnt(0)

; __device__ __forceinline__ void transpose_item(const float* W, int ldw, int k0, int n0, bf16* WT, int Kdst, int dst_row0, LAS float* scr, int lane) {
;     ...
;     for (int i = 0; i < 32; ++i) { const int kk = 2 * i + (lane >> 5); tv[i] = W[(size_t)(k0 + kk) * ldw + n0 + (lane & 31)]; }
; __device__ __forceinline__ void phase_wconv(const Frame& F, const Args& a, int l, unsigned char* wt, unsigned char* wth, int part) {
;     ...
;     for (int it = F.gw; it < NITEMS; it += F.NGW) {
;         int r = it;
;         if (r < I_A) {
;             const int m = r / I_FF, q = r % I_FF, f = m / 3, mm = m % 3;
;             if (!((f ? 2 : 1) & part)) continue;
;             if (mm < 2) {
;                 const float* W = a.in[F.z + (f ? 26 : 3) + mm] + (size_t)l * D * FF;
;                 const int kb = q / 176, nb = q % 176, n0 = 32 * nb;
;                 bf16* dst = (bf16*)(f ? wth + WO_UP2 : wt + WO_UP1);
;                 transpose_item(W, FF, 64 * kb, n0, dst, D, (n0 / 128) * 256 + mm * 128 + (n0 % 128), scr, F.lane);
;             } else {
;                 const float* W = a.in[F.z + (f ? 28 : 5)] + (size_t)l * FF * D;
;                 const int kb = q / 64, nb = q % 64, n0 = 32 * nb;
;                 bf16* dst = (bf16*)(f ? wth + WO_DN2 : wt + WO_DN1);
;                 transpose_item(W, D, 64 * kb, n0, dst, FF, n0, scr, F.lane);
.LBB0_731:
	s_andn2_b64 vcc, exec, s[16:17]
	s_cbranch_vccnz .LBB0_702
	s_add_i32 s16, s30, 0x41ff
	s_cmpk_lt_u32 s16, 0x83ff
	s_cbranch_scc1 .LBB0_702
	s_mul_hi_i32 s16, s30, 0x2e8ba2e9
	s_lshr_b32 s17, s16, 31
	s_ashr_i32 s16, s16, 10
	s_add_i32 s16, s16, s17
	s_mul_i32 s17, s16, 0xffffea00
	s_add_i32 s21, s30, s17
	s_mul_hi_i32 s17, s16, 0x55555556
	s_lshr_b32 s18, s17, 31
	s_add_i32 s17, s17, s18
	s_mul_i32 s17, s17, 3
	s_sub_i32 s20, s16, s17
	s_mov_b64 s[16:17], -1
	s_cmp_gt_i32 s20, 1
	v_lshlrev_b32_e32 v184, 2, v0
	v_add_u32_e32 v31, 0x400, v20
	v_add_u32_e32 v30, 0x800, v20
	v_add_u32_e32 v29, 0xc00, v20
	v_add_u32_e32 v28, 0x1000, v20
	v_add_u32_e32 v27, 0x1400, v20
	v_add_u32_e32 v26, 0x1800, v20
	v_add_u32_e32 v15, 0x1c00, v20
	s_cbranch_scc0 .LBB0_735
	s_load_dwordx2 s[16:17], s[14:15], 0xe0
	v_readlane_b32 s18, v254, 26
	v_readlane_b32 s19, v254, 27
	s_lshl_b64 s[18:19], s[18:19], 2
	s_waitcnt lgkmcnt(0)
	s_add_u32 s31, s16, s18
	s_addc_u32 s19, s17, s19
	s_bfe_u32 s16, s21, 0x60019
	s_add_i32 s16, s21, s16
	s_sext_i32_i16 s17, s16
	s_and_b32 s16, s16, 0xffc0
	s_sub_i32 s16, s21, s16
	s_sext_i32_i16 s16, s16
	s_lshl_b32 s16, s16, 5
	s_and_b32 s18, s17, 0xffffffc0
	s_ashr_i32 s17, s16, 31
	s_lshl_b64 s[34:35], s[16:17], 2
	v_or_b32_e32 v16, s18, v1
	s_add_u32 s34, s31, s34
	s_addc_u32 s35, s19, s35
	v_ashrrev_i32_e32 v17, 31, v16
	v_lshl_add_u64 v[18:19], s[34:35], 0, v[184:185]
	v_lshlrev_b64 v[32:33], 13, v[16:17]
	v_lshl_add_u64 v[32:33], v[18:19], 0, v[32:33]
	global_load_dword v34, v[32:33], off
	v_or_b32_e32 v32, 2, v16
	v_ashrrev_i32_e32 v33, 31, v32
	v_lshlrev_b64 v[32:33], 13, v[32:33]
	v_lshl_add_u64 v[32:33], v[18:19], 0, v[32:33]
	global_load_dword v35, v[32:33], off
	v_or_b32_e32 v32, 4, v16
	v_ashrrev_i32_e32 v33, 31, v32
	v_lshlrev_b64 v[32:33], 13, v[32:33]
	v_lshl_add_u64 v[32:33], v[18:19], 0, v[32:33]
	global_load_dword v36, v[32:33], off
	v_or_b32_e32 v32, 6, v16
	v_ashrrev_i32_e32 v33, 31, v32
	v_lshlrev_b64 v[32:33], 13, v[32:33]
	v_lshl_add_u64 v[32:33], v[18:19], 0, v[32:33]
	global_load_dword v37, v[32:33], off
	v_or_b32_e32 v32, 8, v16
	v_ashrrev_i32_e32 v33, 31, v32
	v_lshlrev_b64 v[32:33], 13, v[32:33]
	v_lshl_add_u64 v[32:33], v[18:19], 0, v[32:33]
	global_load_dword v38, v[32:33], off
	v_or_b32_e32 v32, 10, v16
	v_ashrrev_i32_e32 v33, 31, v32
	v_lshlrev_b64 v[32:33], 13, v[32:33]
	v_lshl_add_u64 v[32:33], v[18:19], 0, v[32:33]
	global_load_dword v39, v[32:33], off
	v_or_b32_e32 v32, 12, v16
	v_ashrrev_i32_e32 v33, 31, v32
	v_lshlrev_b64 v[32:33], 13, v[32:33]
	v_lshl_add_u64 v[32:33], v[18:19], 0, v[32:33]
	global_load_dword v40, v[32:33], off
	v_or_b32_e32 v32, 14, v16
	v_ashrrev_i32_e32 v33, 31, v32
	v_lshlrev_b64 v[32:33], 13, v[32:33]
	v_lshl_add_u64 v[32:33], v[18:19], 0, v[32:33]
	global_load_dword v41, v[32:33], off
	s_waitcnt vmcnt(2)
	v_or_b32_e32 v32, 16, v16
	v_ashrrev_i32_e32 v33, 31, v32
	v_lshlrev_b64 v[32:33], 13, v[32:33]
	v_lshl_add_u64 v[32:33], v[18:19], 0, v[32:33]
	global_load_dword v42, v[32:33], off
	v_or_b32_e32 v32, 18, v16
	v_ashrrev_i32_e32 v33, 31, v32
	v_lshlrev_b64 v[32:33], 13, v[32:33]
	v_lshl_add_u64 v[32:33], v[18:19], 0, v[32:33]
	global_load_dword v43, v[32:33], off
	v_or_b32_e32 v32, 20, v16
	v_ashrrev_i32_e32 v33, 31, v32
	v_lshlrev_b64 v[32:33], 13, v[32:33]
	v_lshl_add_u64 v[32:33], v[18:19], 0, v[32:33]
	global_load_dword v44, v[32:33], off
	v_or_b32_e32 v32, 22, v16
	v_ashrrev_i32_e32 v33, 31, v32
	v_lshlrev_b64 v[32:33], 13, v[32:33]
	v_lshl_add_u64 v[32:33], v[18:19], 0, v[32:33]
	global_load_dword v45, v[32:33], off
	v_or_b32_e32 v32, 24, v16
	v_ashrrev_i32_e32 v33, 31, v32
	v_lshlrev_b64 v[32:33], 13, v[32:33]
	v_lshl_add_u64 v[32:33], v[18:19], 0, v[32:33]
	global_load_dword v46, v[32:33], off
	v_or_b32_e32 v32, 26, v16
	v_ashrrev_i32_e32 v33, 31, v32
	v_lshlrev_b64 v[32:33], 13, v[32:33]
	v_lshl_add_u64 v[32:33], v[18:19], 0, v[32:33]
	global_load_dword v47, v[32:33], off
	v_or_b32_e32 v32, 28, v16
	v_ashrrev_i32_e32 v33, 31, v32
	v_lshlrev_b64 v[32:33], 13, v[32:33]
	v_lshl_add_u64 v[32:33], v[18:19], 0, v[32:33]
	global_load_dword v48, v[32:33], off
	v_or_b32_e32 v32, 30, v16
	v_ashrrev_i32_e32 v33, 31, v32
	v_lshlrev_b64 v[32:33], 13, v[32:33]
	v_lshl_add_u64 v[32:33], v[18:19], 0, v[32:33]
	global_load_dword v49, v[32:33], off
	s_waitcnt vmcnt(2)
	v_or_b32_e32 v32, 32, v16
	v_ashrrev_i32_e32 v33, 31, v32
	v_lshlrev_b64 v[32:33], 13, v[32:33]
	v_lshl_add_u64 v[32:33], v[18:19], 0, v[32:33]
	global_load_dword v50, v[32:33], off
	v_or_b32_e32 v32, 34, v16
	v_ashrrev_i32_e32 v33, 31, v32
	v_lshlrev_b64 v[32:33], 13, v[32:33]
	v_lshl_add_u64 v[32:33], v[18:19], 0, v[32:33]
	global_load_dword v51, v[32:33], off
	v_or_b32_e32 v32, 36, v16
	v_ashrrev_i32_e32 v33, 31, v32
	v_lshlrev_b64 v[32:33], 13, v[32:33]
	v_lshl_add_u64 v[32:33], v[18:19], 0, v[32:33]
	global_load_dword v52, v[32:33], off
	v_or_b32_e32 v32, 38, v16
	v_ashrrev_i32_e32 v33, 31, v32
	v_lshlrev_b64 v[32:33], 13, v[32:33]
	v_lshl_add_u64 v[32:33], v[18:19], 0, v[32:33]
	global_load_dword v53, v[32:33], off
	v_or_b32_e32 v32, 40, v16
	v_ashrrev_i32_e32 v33, 31, v32
	v_lshlrev_b64 v[32:33], 13, v[32:33]
	v_lshl_add_u64 v[32:33], v[18:19], 0, v[32:33]
	global_load_dword v54, v[32:33], off
	v_or_b32_e32 v32, 42, v16
	v_ashrrev_i32_e32 v33, 31, v32
	v_lshlrev_b64 v[32:33], 13, v[32:33]
	v_lshl_add_u64 v[32:33], v[18:19], 0, v[32:33]
	global_load_dword v55, v[32:33], off
	v_or_b32_e32 v32, 44, v16
	v_ashrrev_i32_e32 v33, 31, v32
	v_lshlrev_b64 v[32:33], 13, v[32:33]
	v_lshl_add_u64 v[32:33], v[18:19], 0, v[32:33]
	global_load_dword v56, v[32:33], off
	v_or_b32_e32 v32, 46, v16
	v_ashrrev_i32_e32 v33, 31, v32
	v_lshlrev_b64 v[32:33], 13, v[32:33]
	v_lshl_add_u64 v[32:33], v[18:19], 0, v[32:33]
	global_load_dword v57, v[32:33], off
	s_waitcnt vmcnt(2)
; #define LAS __attribute__((address_space(3)))
; #define LDS_WAIT() asm volatile("s_waitcnt lgkmcnt(0)" ::: "memory")
; __device__ __forceinline__ unsigned pk2(float lo, float hi) { return cvt_pk_bf16(lo, hi); }
; __device__ __forceinline__ void transpose_item(const float* W, int ldw, int k0, int n0, bf16* WT, int Kdst, int dst_row0, LAS float* scr, int lane) {
;     ...
;     for (int i = 0; i < 32; ++i) { const int kk = 2 * i + (lane >> 5); scr[kk * 33 + (lane & 31)] = tv[i]; }
;     LDS_WAIT(); asm volatile("" ::: "memory");
;     const int c = lane & 7;
; #pragma unroll
;     for (int j = 0; j < 4; ++j) { const int n = (lane >> 3) + 8 * j; const LAS float* s = scr + (8 * c) * 33 + n;
;         v4u o; o.x = pk2(s[0 * 33], s[1 * 33]); o.y = pk2(s[2 * 33], s[3 * 33]); o.z = pk2(s[4 * 33], s[5 * 33]); o.w = pk2(s[6 * 33], s[7 * 33]);
;         *(v4u*)(WT + (size_t)(dst_row0 + n) * Kdst + k0 + 8 * c) = o; }
;     LDS_WAIT(); asm volatile("" ::: "memory");
	v_or_b32_e32 v32, 48, v16
	v_ashrrev_i32_e32 v33, 31, v32
	v_lshlrev_b64 v[32:33], 13, v[32:33]
	v_lshl_add_u64 v[32:33], v[18:19], 0, v[32:33]
	global_load_dword v58, v[32:33], off
	v_or_b32_e32 v32, 50, v16
	v_ashrrev_i32_e32 v33, 31, v32
	v_lshlrev_b64 v[32:33], 13, v[32:33]
	v_lshl_add_u64 v[32:33], v[18:19], 0, v[32:33]
	global_load_dword v59, v[32:33], off
	v_or_b32_e32 v32, 52, v16
	v_ashrrev_i32_e32 v33, 31, v32
	v_lshlrev_b64 v[32:33], 13, v[32:33]
	v_lshl_add_u64 v[32:33], v[18:19], 0, v[32:33]
	global_load_dword v60, v[32:33], off
	v_or_b32_e32 v32, 54, v16
	v_ashrrev_i32_e32 v33, 31, v32
	v_lshlrev_b64 v[32:33], 13, v[32:33]
	v_lshl_add_u64 v[32:33], v[18:19], 0, v[32:33]
	global_load_dword v61, v[32:33], off
	v_or_b32_e32 v32, 56, v16
	v_ashrrev_i32_e32 v33, 31, v32
	v_lshlrev_b64 v[32:33], 13, v[32:33]
	v_lshl_add_u64 v[32:33], v[18:19], 0, v[32:33]
	global_load_dword v62, v[32:33], off
	v_or_b32_e32 v32, 58, v16
	v_ashrrev_i32_e32 v33, 31, v32
	v_lshlrev_b64 v[32:33], 13, v[32:33]
	v_lshl_add_u64 v[32:33], v[18:19], 0, v[32:33]
	global_load_dword v63, v[32:33], off
	v_or_b32_e32 v32, 60, v16
	v_or_b32_e32 v16, 62, v16
	v_ashrrev_i32_e32 v33, 31, v32
	v_ashrrev_i32_e32 v17, 31, v16
	v_lshlrev_b64 v[32:33], 13, v[32:33]
	v_lshlrev_b64 v[16:17], 13, v[16:17]
	v_lshl_add_u64 v[32:33], v[18:19], 0, v[32:33]
	v_lshl_add_u64 v[16:17], v[18:19], 0, v[16:17]
	global_load_dword v32, v[32:33], off
	s_ashr_i32 s19, s18, 31
	global_load_dword v16, v[16:17], off
	s_waitcnt vmcnt(30)
	ds_write2_b32 v20, v34, v35 offset1:66
	s_waitcnt vmcnt(28)
	ds_write2_b32 v20, v36, v37 offset0:132 offset1:198
	s_waitcnt vmcnt(26)
	ds_write2_b32 v31, v38, v39 offset0:8 offset1:74
	s_waitcnt vmcnt(24)
	ds_write2_b32 v31, v40, v41 offset0:140 offset1:206
	s_waitcnt vmcnt(22)
	ds_write2_b32 v30, v42, v43 offset0:16 offset1:82
	s_waitcnt vmcnt(20)
	ds_write2_b32 v30, v44, v45 offset0:148 offset1:214
	s_waitcnt vmcnt(18)
	ds_write2_b32 v29, v46, v47 offset0:24 offset1:90
	s_waitcnt vmcnt(16)
	ds_write2_b32 v29, v48, v49 offset0:156 offset1:222
	s_waitcnt vmcnt(14)
	ds_write2_b32 v28, v50, v51 offset0:32 offset1:98
	s_waitcnt vmcnt(12)
	ds_write2_b32 v28, v52, v53 offset0:164 offset1:230
	s_waitcnt vmcnt(10)
	ds_write2_b32 v27, v54, v55 offset0:40 offset1:106
	s_waitcnt vmcnt(8)
	ds_write2_b32 v27, v56, v57 offset0:172 offset1:238
	s_waitcnt vmcnt(6)
	ds_write2_b32 v26, v58, v59 offset0:48 offset1:114
	s_waitcnt vmcnt(4)
	ds_write2_b32 v26, v60, v61 offset0:180 offset1:246
	s_waitcnt vmcnt(2)
	ds_write2_b32 v15, v62, v63 offset0:56 offset1:122
	s_waitcnt vmcnt(0)
	ds_write2_b32 v15, v32, v16 offset0:188 offset1:254
	s_waitcnt lgkmcnt(0)
	ds_read2_b32 v[34:35], v22 offset0:33 offset1:41
	ds_read2_b32 v[36:37], v22 offset1:8
	ds_read2_b32 v[38:39], v22 offset0:66 offset1:74
	ds_read2_b32 v[40:41], v22 offset0:99 offset1:107
	ds_read2_b32 v[42:43], v22 offset0:132 offset1:140
	ds_read2_b32 v[44:45], v22 offset0:165 offset1:173
	ds_read2_b32 v[46:47], v22 offset0:198 offset1:206
	ds_read2_b32 v[48:49], v22 offset0:231 offset1:239
	v_lshl_add_u64 v[32:33], s[18:19], 1, v[10:11]
	s_waitcnt lgkmcnt(6)
	v_cvt_pk_bf16_f32 v16, v36, v34
	v_or_b32_e32 v34, s16, v21
	v_mul_i32_i24_e32 v50, 0x2c00, v34
	v_ashrrev_i32_e32 v51, 31, v50
	v_or_b32_e32 v34, s16, v23
	s_waitcnt lgkmcnt(4)
	v_cvt_pk_bf16_f32 v17, v38, v40
	s_waitcnt lgkmcnt(2)
	v_cvt_pk_bf16_f32 v18, v42, v44
	s_waitcnt lgkmcnt(0)
	v_cvt_pk_bf16_f32 v19, v46, v48
	v_lshl_add_u64 v[50:51], v[32:33], 0, v[50:51]
	v_mul_i32_i24_e32 v34, 0x2c00, v34
	global_store_dwordx4 v[50:51], v[16:19], off
	s_nop 1
	v_cvt_pk_bf16_f32 v16, v37, v35
	v_ashrrev_i32_e32 v35, 31, v34
	v_cvt_pk_bf16_f32 v17, v39, v41
	v_cvt_pk_bf16_f32 v18, v43, v45
	v_cvt_pk_bf16_f32 v19, v47, v49
	v_lshl_add_u64 v[34:35], v[32:33], 0, v[34:35]
	global_store_dwordx4 v[34:35], v[16:19], off
	ds_read2_b32 v[34:35], v22 offset0:16 offset1:24
	ds_read2_b32 v[36:37], v22 offset0:49 offset1:57
	ds_read2_b32 v[38:39], v22 offset0:82 offset1:90
	ds_read2_b32 v[40:41], v22 offset0:115 offset1:123
	ds_read2_b32 v[42:43], v22 offset0:148 offset1:156
	ds_read2_b32 v[44:45], v22 offset0:181 offset1:189
	ds_read2_b32 v[46:47], v22 offset0:214 offset1:222
	ds_read2_b32 v[48:49], v22 offset0:247 offset1:255
	s_waitcnt lgkmcnt(6)
	v_cvt_pk_bf16_f32 v16, v34, v36
	v_or_b32_e32 v34, s16, v24
	v_mul_i32_i24_e32 v50, 0x2c00, v34
	v_ashrrev_i32_e32 v51, 31, v50
	v_or_b32_e32 v34, s16, v25
	s_waitcnt lgkmcnt(4)
	v_cvt_pk_bf16_f32 v17, v38, v40
	s_waitcnt lgkmcnt(2)
	v_cvt_pk_bf16_f32 v18, v42, v44
	s_waitcnt lgkmcnt(0)
	v_cvt_pk_bf16_f32 v19, v46, v48
	v_lshl_add_u64 v[50:51], v[32:33], 0, v[50:51]
	v_mul_i32_i24_e32 v34, 0x2c00, v34
	global_store_dwordx4 v[50:51], v[16:19], off
	s_mov_b64 s[16:17], 0
	s_nop 0
	v_cvt_pk_bf16_f32 v16, v35, v37
	v_ashrrev_i32_e32 v35, 31, v34
	v_cvt_pk_bf16_f32 v17, v39, v41
	v_cvt_pk_bf16_f32 v18, v43, v45
	v_cvt_pk_bf16_f32 v19, v47, v49
	v_lshl_add_u64 v[32:33], v[32:33], 0, v[34:35]
	global_store_dwordx4 v[32:33], v[16:19], off
	s_waitcnt lgkmcnt(0)
; __device__ __forceinline__ void transpose_item(const float* W, int ldw, int k0, int n0, bf16* WT, int Kdst, int dst_row0, LAS float* scr, int lane) {
;     ...
;     for (int i = 0; i < 32; ++i) { const int kk = 2 * i + (lane >> 5); tv[i] = W[(size_t)(k0 + kk) * ldw + n0 + (lane & 31)]; }
; __device__ __forceinline__ void phase_wconv(const Frame& F, const Args& a, int l, unsigned char* wt, unsigned char* wth, int part) {
;     ...
;             if (mm < 2) {
;                 const float* W = a.in[F.z + (f ? 26 : 3) + mm] + (size_t)l * D * FF;
;                 const int kb = q / 176, nb = q % 176, n0 = 32 * nb;
;                 bf16* dst = (bf16*)(f ? wth + WO_UP2 : wt + WO_UP1);
;                 transpose_item(W, FF, 64 * kb, n0, dst, D, (n0 / 128) * 256 + mm * 128 + (n0 % 128), scr, F.lane);
.LBB0_735:
	s_andn2_b64 vcc, exec, s[16:17]
	s_cbranch_vccnz .LBB0_702
	s_add_i32 s16, s27, s20
	s_ashr_i32 s17, s16, 31
	s_lshl_b64 s[16:17], s[16:17], 3
	v_readlane_b32 s18, v254, 1
	v_readlane_b32 s19, v254, 2
	s_add_u32 s16, s18, s16
	s_addc_u32 s17, s19, s17
	s_load_dwordx2 s[16:17], s[16:17], 0x0
	v_readlane_b32 s18, v254, 26
	v_readlane_b32 s19, v254, 27
	s_lshl_b64 s[18:19], s[18:19], 2
	s_waitcnt lgkmcnt(0)
	s_add_u32 s31, s16, s18
	s_mul_i32 s16, s21, 0xba3
	s_addc_u32 s17, s17, s19
	s_lshr_b32 s18, s16, 31
	s_ashr_i32 s16, s16, 19
	s_add_i32 s16, s16, s18
	s_mul_i32 s18, s16, 0xb0
	s_sub_i32 s18, s21, s18
	s_sext_i32_i16 s19, s18
	s_bfe_u32 s21, s19, 0x2001d
	s_lshl_b32 s34, s19, 5
	s_add_i32 s18, s18, s21
	s_bfe_u32 s19, s19, 0x70013
	s_sext_i32_i16 s18, s18
	s_add_i32 s19, s34, s19
	s_lshl_b32 s18, s18, 6
	s_and_b32 s19, s19, 0xff80
	s_and_b32 s18, s18, 0xffffff00
	s_lshl_b32 s20, s20, 7
	s_sub_i32 s19, s34, s19
	s_add_i32 s18, s18, s20
	s_sext_i32_i16 s19, s19
	s_ashr_i32 s35, s34, 31
	s_lshl_b32 s16, s16, 6
	s_add_i32 s18, s18, s19
	s_lshl_b64 s[20:21], s[34:35], 2
	v_or_b32_e32 v18, s16, v1
	s_add_u32 s20, s31, s20
	s_addc_u32 s21, s17, s21
	v_mul_i32_i24_e32 v18, 0x5800, v18
	v_lshl_add_u64 v[16:17], s[20:21], 0, v[184:185]
	v_ashrrev_i32_e32 v19, 31, v18
	v_lshl_add_u64 v[16:17], v[16:17], 0, v[18:19]
	s_mov_b32 s17, 0xb000
	v_add_co_u32_e32 v18, vcc, s17, v16
	s_mov_b32 s17, 0x16000
	s_nop 0
	v_addc_co_u32_e32 v19, vcc, 0, v17, vcc
	global_load_dword v32, v[16:17], off
	global_load_dword v33, v[18:19], off
	v_add_co_u32_e32 v18, vcc, s17, v16
	s_mov_b32 s17, 0x21000
	s_nop 0
	v_addc_co_u32_e32 v19, vcc, 0, v17, vcc
	global_load_dword v34, v[18:19], off
	v_add_co_u32_e32 v18, vcc, s17, v16
	s_mov_b32 s17, 0x2c000
	s_nop 0
	v_addc_co_u32_e32 v19, vcc, 0, v17, vcc
	global_load_dword v35, v[18:19], off
	v_add_co_u32_e32 v18, vcc, s17, v16
	s_mov_b32 s17, 0x37000
	s_nop 0
	v_addc_co_u32_e32 v19, vcc, 0, v17, vcc
	global_load_dword v36, v[18:19], off
	v_add_co_u32_e32 v18, vcc, s17, v16
	s_mov_b32 s17, 0x42000
	s_nop 0
	v_addc_co_u32_e32 v19, vcc, 0, v17, vcc
	global_load_dword v37, v[18:19], off
	v_add_co_u32_e32 v18, vcc, s17, v16
	s_mov_b32 s17, 0x4d000
	s_nop 0
	v_addc_co_u32_e32 v19, vcc, 0, v17, vcc
	global_load_dword v38, v[18:19], off
	v_add_co_u32_e32 v18, vcc, s17, v16
	s_mov_b32 s17, 0x58000
	s_nop 0
	v_addc_co_u32_e32 v19, vcc, 0, v17, vcc
	global_load_dword v39, v[18:19], off
	s_waitcnt vmcnt(2)
	v_add_co_u32_e32 v18, vcc, s17, v16
	s_mov_b32 s17, 0x63000
	s_nop 0
	v_addc_co_u32_e32 v19, vcc, 0, v17, vcc
	global_load_dword v40, v[18:19], off
	v_add_co_u32_e32 v18, vcc, s17, v16
	s_mov_b32 s17, 0x6e000
	s_nop 0
	v_addc_co_u32_e32 v19, vcc, 0, v17, vcc
	global_load_dword v41, v[18:19], off
	v_add_co_u32_e32 v18, vcc, s17, v16
	s_mov_b32 s17, 0x79000
	s_nop 0
	v_addc_co_u32_e32 v19, vcc, 0, v17, vcc
	global_load_dword v42, v[18:19], off
	v_add_co_u32_e32 v18, vcc, s17, v16
	s_mov_b32 s17, 0x84000
	s_nop 0
	v_addc_co_u32_e32 v19, vcc, 0, v17, vcc
	global_load_dword v43, v[18:19], off
	v_add_co_u32_e32 v18, vcc, s17, v16
	s_mov_b32 s17, 0x8f000
	s_nop 0
	v_addc_co_u32_e32 v19, vcc, 0, v17, vcc
	global_load_dword v44, v[18:19], off
	v_add_co_u32_e32 v18, vcc, s17, v16
	s_mov_b32 s17, 0x9a000
	s_nop 0
	v_addc_co_u32_e32 v19, vcc, 0, v17, vcc
	global_load_dword v45, v[18:19], off
	v_add_co_u32_e32 v18, vcc, s17, v16
	s_mov_b32 s17, 0xa5000
	s_nop 0
	v_addc_co_u32_e32 v19, vcc, 0, v17, vcc
	global_load_dword v46, v[18:19], off
	v_add_co_u32_e32 v18, vcc, s17, v16
	s_mov_b32 s17, 0xb0000
	s_nop 0
	v_addc_co_u32_e32 v19, vcc, 0, v17, vcc
	global_load_dword v47, v[18:19], off
	s_waitcnt vmcnt(2)
	v_add_co_u32_e32 v18, vcc, s17, v16
	s_mov_b32 s17, 0xbb000
	s_nop 0
	v_addc_co_u32_e32 v19, vcc, 0, v17, vcc
	global_load_dword v48, v[18:19], off
	v_add_co_u32_e32 v18, vcc, s17, v16
	s_mov_b32 s17, 0xc6000
	s_nop 0
	v_addc_co_u32_e32 v19, vcc, 0, v17, vcc
	global_load_dword v49, v[18:19], off
	v_add_co_u32_e32 v18, vcc, s17, v16
	s_mov_b32 s17, 0xd1000
	s_nop 0
	v_addc_co_u32_e32 v19, vcc, 0, v17, vcc
	global_load_dword v50, v[18:19], off
	v_add_co_u32_e32 v18, vcc, s17, v16
	s_mov_b32 s17, 0xdc000
	s_nop 0
	v_addc_co_u32_e32 v19, vcc, 0, v17, vcc
	global_load_dword v51, v[18:19], off
	v_add_co_u32_e32 v18, vcc, s17, v16
	s_mov_b32 s17, 0xe7000
	s_nop 0
	v_addc_co_u32_e32 v19, vcc, 0, v17, vcc
	global_load_dword v52, v[18:19], off
	v_add_co_u32_e32 v18, vcc, s17, v16
	s_mov_b32 s17, 0xf2000
	s_nop 0
	v_addc_co_u32_e32 v19, vcc, 0, v17, vcc
	global_load_dword v53, v[18:19], off
	v_add_co_u32_e32 v18, vcc, s17, v16
	s_mov_b32 s17, 0xfd000
	s_nop 0
	v_addc_co_u32_e32 v19, vcc, 0, v17, vcc
	global_load_dword v54, v[18:19], off
	v_add_co_u32_e32 v18, vcc, s17, v16
	s_mov_b32 s17, 0x108000
	s_nop 0
	v_addc_co_u32_e32 v19, vcc, 0, v17, vcc
	global_load_dword v55, v[18:19], off
	s_waitcnt vmcnt(2)
; #define LAS __attribute__((address_space(3)))
; #define LDS_WAIT() asm volatile("s_waitcnt lgkmcnt(0)" ::: "memory")
; __device__ __forceinline__ unsigned pk2(float lo, float hi) { return cvt_pk_bf16(lo, hi); }
; __device__ __forceinline__ void transpose_item(const float* W, int ldw, int k0, int n0, bf16* WT, int Kdst, int dst_row0, LAS float* scr, int lane) {
;     ...
;     for (int i = 0; i < 32; ++i) { const int kk = 2 * i + (lane >> 5); scr[kk * 33 + (lane & 31)] = tv[i]; }
;     LDS_WAIT(); asm volatile("" ::: "memory");
;     const int c = lane & 7;
; #pragma unroll
;     for (int j = 0; j < 4; ++j) { const int n = (lane >> 3) + 8 * j; const LAS float* s = scr + (8 * c) * 33 + n;
;         v4u o; o.x = pk2(s[0 * 33], s[1 * 33]); o.y = pk2(s[2 * 33], s[3 * 33]); o.z = pk2(s[4 * 33], s[5 * 33]); o.w = pk2(s[6 * 33], s[7 * 33]);
;         *(v4u*)(WT + (size_t)(dst_row0 + n) * Kdst + k0 + 8 * c) = o; }
;     LDS_WAIT(); asm volatile("" ::: "memory");
	v_add_co_u32_e32 v18, vcc, s17, v16
	s_mov_b32 s17, 0x113000
	s_nop 0
	v_addc_co_u32_e32 v19, vcc, 0, v17, vcc
	global_load_dword v56, v[18:19], off
	v_add_co_u32_e32 v18, vcc, s17, v16
	s_mov_b32 s17, 0x11e000
	s_nop 0
	v_addc_co_u32_e32 v19, vcc, 0, v17, vcc
	global_load_dword v57, v[18:19], off
	v_add_co_u32_e32 v18, vcc, s17, v16
	s_mov_b32 s17, 0x129000
	s_nop 0
	v_addc_co_u32_e32 v19, vcc, 0, v17, vcc
	global_load_dword v58, v[18:19], off
	v_add_co_u32_e32 v18, vcc, s17, v16
	s_mov_b32 s17, 0x134000
	s_nop 0
	v_addc_co_u32_e32 v19, vcc, 0, v17, vcc
	global_load_dword v59, v[18:19], off
	v_add_co_u32_e32 v18, vcc, s17, v16
	s_mov_b32 s17, 0x13f000
	s_nop 0
	v_addc_co_u32_e32 v19, vcc, 0, v17, vcc
	global_load_dword v60, v[18:19], off
	v_add_co_u32_e32 v18, vcc, s17, v16
	s_mov_b32 s17, 0x14a000
	s_nop 0
	v_addc_co_u32_e32 v19, vcc, 0, v17, vcc
	global_load_dword v61, v[18:19], off
	v_add_co_u32_e32 v18, vcc, s17, v16
	s_mov_b32 s17, 0x155000
	s_nop 0
	v_addc_co_u32_e32 v19, vcc, 0, v17, vcc
	v_add_co_u32_e32 v16, vcc, s17, v16
	global_load_dword v18, v[18:19], off
	s_nop 0
	v_addc_co_u32_e32 v17, vcc, 0, v17, vcc
	global_load_dword v16, v[16:17], off
	s_waitcnt vmcnt(30)
	ds_write2_b32 v20, v32, v33 offset1:66
	s_waitcnt vmcnt(28)
	ds_write2_b32 v20, v34, v35 offset0:132 offset1:198
	s_waitcnt vmcnt(26)
	ds_write2_b32 v31, v36, v37 offset0:8 offset1:74
	s_waitcnt vmcnt(24)
	ds_write2_b32 v31, v38, v39 offset0:140 offset1:206
	s_waitcnt vmcnt(22)
	ds_write2_b32 v30, v40, v41 offset0:16 offset1:82
	s_waitcnt vmcnt(20)
	ds_write2_b32 v30, v42, v43 offset0:148 offset1:214
	s_waitcnt vmcnt(18)
	ds_write2_b32 v29, v44, v45 offset0:24 offset1:90
	s_waitcnt vmcnt(16)
	ds_write2_b32 v29, v46, v47 offset0:156 offset1:222
	s_waitcnt vmcnt(14)
	ds_write2_b32 v28, v48, v49 offset0:32 offset1:98
	s_waitcnt vmcnt(12)
	ds_write2_b32 v28, v50, v51 offset0:164 offset1:230
	s_waitcnt vmcnt(10)
	ds_write2_b32 v27, v52, v53 offset0:40 offset1:106
	s_waitcnt vmcnt(8)
	ds_write2_b32 v27, v54, v55 offset0:172 offset1:238
	s_waitcnt vmcnt(6)
	ds_write2_b32 v26, v56, v57 offset0:48 offset1:114
	s_waitcnt vmcnt(4)
	ds_write2_b32 v26, v58, v59 offset0:180 offset1:246
	s_waitcnt vmcnt(2)
	ds_write2_b32 v15, v60, v61 offset0:56 offset1:122
	s_waitcnt vmcnt(0)
	ds_write2_b32 v15, v18, v16 offset0:188 offset1:254
	s_waitcnt lgkmcnt(0)
	ds_read2_b32 v[28:29], v22 offset0:33 offset1:41
	ds_read2_b32 v[30:31], v22 offset1:8
	ds_read2_b32 v[32:33], v22 offset0:66 offset1:74
	ds_read2_b32 v[34:35], v22 offset0:99 offset1:107
	ds_read2_b32 v[36:37], v22 offset0:132 offset1:140
	ds_read2_b32 v[38:39], v22 offset0:165 offset1:173
	ds_read2_b32 v[40:41], v22 offset0:198 offset1:206
	ds_read2_b32 v[42:43], v22 offset0:231 offset1:239
	v_or_b32_e32 v44, s18, v21
	s_ashr_i32 s17, s16, 31
	v_ashrrev_i32_e32 v45, 31, v44
	v_lshl_add_u64 v[26:27], s[16:17], 1, v[12:13]
	v_lshlrev_b64 v[44:45], 12, v[44:45]
	s_waitcnt lgkmcnt(6)
	v_cvt_pk_bf16_f32 v16, v30, v28
	s_waitcnt lgkmcnt(4)
	v_cvt_pk_bf16_f32 v17, v32, v34
	s_waitcnt lgkmcnt(2)
	v_cvt_pk_bf16_f32 v18, v36, v38
	s_waitcnt lgkmcnt(0)
	v_cvt_pk_bf16_f32 v19, v40, v42
	v_lshl_add_u64 v[44:45], v[26:27], 0, v[44:45]
	v_or_b32_e32 v28, s18, v23
	global_store_dwordx4 v[44:45], v[16:19], off
	v_or_b32_e32 v44, s18, v24
	v_ashrrev_i32_e32 v45, 31, v44
	v_cvt_pk_bf16_f32 v16, v31, v29
	v_ashrrev_i32_e32 v29, 31, v28
	v_lshlrev_b64 v[28:29], 12, v[28:29]
	v_cvt_pk_bf16_f32 v17, v33, v35
	v_cvt_pk_bf16_f32 v18, v37, v39
	v_cvt_pk_bf16_f32 v19, v41, v43
	v_lshl_add_u64 v[28:29], v[26:27], 0, v[28:29]
	global_store_dwordx4 v[28:29], v[16:19], off
	ds_read2_b32 v[28:29], v22 offset0:49 offset1:57
	ds_read2_b32 v[30:31], v22 offset0:16 offset1:24
	ds_read2_b32 v[32:33], v22 offset0:82 offset1:90
	ds_read2_b32 v[34:35], v22 offset0:115 offset1:123
	ds_read2_b32 v[36:37], v22 offset0:148 offset1:156
	ds_read2_b32 v[38:39], v22 offset0:181 offset1:189
	ds_read2_b32 v[40:41], v22 offset0:214 offset1:222
	ds_read2_b32 v[42:43], v22 offset0:247 offset1:255
	v_lshlrev_b64 v[44:45], 12, v[44:45]
	s_waitcnt lgkmcnt(6)
	v_cvt_pk_bf16_f32 v16, v30, v28
	s_waitcnt lgkmcnt(4)
	v_cvt_pk_bf16_f32 v17, v32, v34
	s_waitcnt lgkmcnt(2)
	v_cvt_pk_bf16_f32 v18, v36, v38
	s_waitcnt lgkmcnt(0)
	v_cvt_pk_bf16_f32 v19, v40, v42
	v_lshl_add_u64 v[44:45], v[26:27], 0, v[44:45]
	v_or_b32_e32 v28, s18, v25
	global_store_dwordx4 v[44:45], v[16:19], off
	s_nop 1
	v_cvt_pk_bf16_f32 v16, v31, v29
	v_ashrrev_i32_e32 v29, 31, v28
	v_lshlrev_b64 v[28:29], 12, v[28:29]
	v_cvt_pk_bf16_f32 v17, v33, v35
	v_cvt_pk_bf16_f32 v18, v37, v39
	v_cvt_pk_bf16_f32 v19, v41, v43
	v_lshl_add_u64 v[26:27], v[26:27], 0, v[28:29]
	global_store_dwordx4 v[26:27], v[16:19], off
	s_waitcnt lgkmcnt(0)
	s_branch .LBB0_702

; __device__ __forceinline__ void transpose_item(const float* W, int ldw, int k0, int n0, bf16* WT, int Kdst, int dst_row0, LAS float* scr, int lane) {
;     ...
;     for (int i = 0; i < 32; ++i) { const int kk = 2 * i + (lane >> 5); tv[i] = W[(size_t)(k0 + kk) * ldw + n0 + (lane & 31)]; }
; __device__ __forceinline__ void phase_wconv(const Frame& F, const Args& a, int l, unsigned char* wt, unsigned char* wth, int part) {
;     ...
;         if (r < I_IN) {
;             const float* W = a.in[F.z + 7] + (size_t)l * D * 15744;
;             const int kb = r / 492, nb = r % 492, n0 = 32 * nb;
;             if (!(((n0 >= 7680 && n0 < 9600) ? 1 : 2) & part)) continue;
;             bf16* dst; int row;
;             if (n0 < 4608) { dst = (bf16*)(wth + WO_ATT); row = n0; }
;             else if (n0 < 7680) { dst = (bf16*)(wth + WO_RET); row = n0 - 4608; }
;             else if (n0 < 9600) { dst = (bf16*)(wth + WO_CF); row = n0 - 7680; }
;             else { dst = (bf16*)(wth + WO_GATE); row = n0 - 9600; }
;             transpose_item(W, 15744, 64 * kb, n0, dst, D, row, scr, F.lane);
.LBB0_744:
	s_cmp_gt_i32 s23, 0x83ff
	s_mov_b64 s[6:7], -1
	s_cbranch_scc0 .LBB0_749
	s_mov_b64 s[6:7], 0
	s_cmpk_gt_u32 s23, 0xc17f
	s_mov_b64 s[8:9], 0
	s_cbranch_scc1 .LBB0_749
	s_add_i32 s8, s23, 0x7c00
	s_bfe_u32 s9, s8, 0xe0002
	s_mulk_i32 s9, 0x429b
	s_lshr_b32 s12, s9, 21
	s_mul_i32 s9, s12, 0x1ec
	s_sub_i32 s8, s8, s9
	s_add_i32 s9, s8, 0xfed4
	s_and_b32 s9, s9, 0xffff
	s_cmpk_lt_u32 s9, 0xffc4
	s_cbranch_scc1 .LBB0_748
	s_and_b32 s9, 0xffff, s8
	s_lshl_b32 s8, s8, 5
	s_and_b32 s13, s8, 0xffe0
	s_cmpk_lt_u32 s9, 0x12c
	s_load_dwordx2 s[14:15], s[4:5], 0x38
	s_mov_b32 s9, 0xa400000
	s_movk_i32 s8, 0xe200
	s_cselect_b32 s9, s9, 0xac00000
	s_cselect_b32 s8, s8, 0xffffda80
	s_add_u32 s9, s50, s9
	s_addc_u32 s11, s51, 0
	s_lshl_b32 s12, s12, 6
	s_add_i32 s8, s8, s13
	s_and_b32 s12, s12, 0x3fc0
	s_lshl_b32 s13, s13, 2
	s_waitcnt lgkmcnt(0)
	s_add_u32 s14, s14, s13
	v_or_b32_e32 v7, s12, v1
	s_addc_u32 s15, s15, 0
	v_lshlrev_b32_e32 v184, 2, v0
	v_lshl_add_u64 v[8:9], s[14:15], 0, v[184:185]
	v_mul_u32_u24_e32 v184, 0xf600, v7
	v_lshl_add_u64 v[8:9], v[8:9], 0, v[184:185]
	s_mov_b32 s13, 0x7b00000
	v_add_co_u32_e32 v10, vcc, s13, v8
	s_mov_b32 s13, 0x7b1e000
	s_nop 0
	v_addc_co_u32_e32 v11, vcc, 0, v9, vcc
	global_load_dword v7, v[10:11], off
	v_add_co_u32_e32 v10, vcc, s13, v8
	s_mov_b32 s13, 0x7b3d000
	s_nop 0
	v_addc_co_u32_e32 v11, vcc, 0, v9, vcc
	global_load_dword v18, v[10:11], off offset:3072
	v_add_co_u32_e32 v10, vcc, s13, v8
	s_mov_b32 s13, 0x7b5c000
	s_nop 0
	v_addc_co_u32_e32 v11, vcc, 0, v9, vcc
	global_load_dword v19, v[10:11], off offset:2048
	v_add_co_u32_e32 v10, vcc, s13, v8
	s_mov_b32 s13, 0x7b7b000
	s_nop 0
	v_addc_co_u32_e32 v11, vcc, 0, v9, vcc
	global_load_dword v20, v[10:11], off offset:1024
	v_add_co_u32_e32 v10, vcc, s13, v8
	s_mov_b32 s13, 0x7b99000
	s_nop 0
	v_addc_co_u32_e32 v11, vcc, 0, v9, vcc
	global_load_dword v21, v[10:11], off
	v_add_co_u32_e32 v10, vcc, s13, v8
	s_mov_b32 s13, 0x7bb8000
	s_nop 0
	v_addc_co_u32_e32 v11, vcc, 0, v9, vcc
	global_load_dword v22, v[10:11], off offset:3072
	v_add_co_u32_e32 v10, vcc, s13, v8
	s_mov_b32 s13, 0x7bd7000
	s_nop 0
	v_addc_co_u32_e32 v11, vcc, 0, v9, vcc
	global_load_dword v23, v[10:11], off offset:2048
	v_add_co_u32_e32 v10, vcc, s13, v8
	s_mov_b32 s13, 0x7bf6000
	s_nop 0
	v_addc_co_u32_e32 v11, vcc, 0, v9, vcc
	global_load_dword v24, v[10:11], off offset:1024
	s_waitcnt vmcnt(2)
	v_add_co_u32_e32 v10, vcc, s13, v8
	s_mov_b32 s13, 0x7c14000
	s_nop 0
	v_addc_co_u32_e32 v11, vcc, 0, v9, vcc
	global_load_dword v25, v[10:11], off
	v_add_co_u32_e32 v10, vcc, s13, v8
	s_mov_b32 s13, 0x7c33000
	s_nop 0
	v_addc_co_u32_e32 v11, vcc, 0, v9, vcc
	global_load_dword v26, v[10:11], off offset:3072
	v_add_co_u32_e32 v10, vcc, s13, v8
	s_mov_b32 s13, 0x7c52000
	s_nop 0
	v_addc_co_u32_e32 v11, vcc, 0, v9, vcc
	global_load_dword v27, v[10:11], off offset:2048
	v_add_co_u32_e32 v10, vcc, s13, v8
	s_mov_b32 s13, 0x7c71000
	s_nop 0
	v_addc_co_u32_e32 v11, vcc, 0, v9, vcc
	global_load_dword v28, v[10:11], off offset:1024
	v_add_co_u32_e32 v10, vcc, s13, v8
	s_mov_b32 s13, 0x7c8f000
	s_nop 0
	v_addc_co_u32_e32 v11, vcc, 0, v9, vcc
	global_load_dword v29, v[10:11], off
	v_add_co_u32_e32 v10, vcc, s13, v8
	s_mov_b32 s13, 0x7cae000
	s_nop 0
	v_addc_co_u32_e32 v11, vcc, 0, v9, vcc
	global_load_dword v30, v[10:11], off offset:3072
	v_add_co_u32_e32 v10, vcc, s13, v8
	s_mov_b32 s13, 0x7ccd000
	s_nop 0
	v_addc_co_u32_e32 v11, vcc, 0, v9, vcc
	global_load_dword v31, v[10:11], off offset:2048
	v_add_co_u32_e32 v10, vcc, s13, v8
	s_mov_b32 s13, 0x7cec000
	s_nop 0
	v_addc_co_u32_e32 v11, vcc, 0, v9, vcc
	global_load_dword v32, v[10:11], off offset:1024
	s_waitcnt vmcnt(2)
	v_add_co_u32_e32 v10, vcc, s13, v8
	s_mov_b32 s13, 0x7d0a000
	s_nop 0
	v_addc_co_u32_e32 v11, vcc, 0, v9, vcc
	global_load_dword v33, v[10:11], off
	v_add_co_u32_e32 v10, vcc, s13, v8
	s_mov_b32 s13, 0x7d29000
	s_nop 0
	v_addc_co_u32_e32 v11, vcc, 0, v9, vcc
	global_load_dword v34, v[10:11], off offset:3072
	v_add_co_u32_e32 v10, vcc, s13, v8
	s_mov_b32 s13, 0x7d48000
	s_nop 0
	v_addc_co_u32_e32 v11, vcc, 0, v9, vcc
	global_load_dword v35, v[10:11], off offset:2048
	v_add_co_u32_e32 v10, vcc, s13, v8
	s_mov_b32 s13, 0x7d67000
	s_nop 0
	v_addc_co_u32_e32 v11, vcc, 0, v9, vcc
	global_load_dword v36, v[10:11], off offset:1024
	v_add_co_u32_e32 v10, vcc, s13, v8
	s_mov_b32 s13, 0x7d85000
	s_nop 0
	v_addc_co_u32_e32 v11, vcc, 0, v9, vcc
	global_load_dword v37, v[10:11], off
	v_add_co_u32_e32 v10, vcc, s13, v8
	s_mov_b32 s13, 0x7da4000
	s_nop 0
	v_addc_co_u32_e32 v11, vcc, 0, v9, vcc
	global_load_dword v38, v[10:11], off offset:3072
	v_add_co_u32_e32 v10, vcc, s13, v8
	s_mov_b32 s13, 0x7dc3000
	s_nop 0
	v_addc_co_u32_e32 v11, vcc, 0, v9, vcc
	global_load_dword v39, v[10:11], off offset:2048
	v_add_co_u32_e32 v10, vcc, s13, v8
	s_mov_b32 s13, 0x7de2000
	s_nop 0
	v_addc_co_u32_e32 v11, vcc, 0, v9, vcc
	global_load_dword v40, v[10:11], off offset:1024
	s_waitcnt vmcnt(2)
; #define LAS __attribute__((address_space(3)))
; #define LDS_WAIT() asm volatile("s_waitcnt lgkmcnt(0)" ::: "memory")
; __device__ __forceinline__ unsigned pk2(float lo, float hi) { return cvt_pk_bf16(lo, hi); }
; __device__ __forceinline__ void transpose_item(const float* W, int ldw, int k0, int n0, bf16* WT, int Kdst, int dst_row0, LAS float* scr, int lane) {
;     ...
;     for (int i = 0; i < 32; ++i) { const int kk = 2 * i + (lane >> 5); scr[kk * 33 + (lane & 31)] = tv[i]; }
;     LDS_WAIT(); asm volatile("" ::: "memory");
;     const int c = lane & 7;
; #pragma unroll
;     for (int j = 0; j < 4; ++j) { const int n = (lane >> 3) + 8 * j; const LAS float* s = scr + (8 * c) * 33 + n;
;         v4u o; o.x = pk2(s[0 * 33], s[1 * 33]); o.y = pk2(s[2 * 33], s[3 * 33]); o.z = pk2(s[4 * 33], s[5 * 33]); o.w = pk2(s[6 * 33], s[7 * 33]);
;         *(v4u*)(WT + (size_t)(dst_row0 + n) * Kdst + k0 + 8 * c) = o; }
;     LDS_WAIT(); asm volatile("" ::: "memory");
	v_add_co_u32_e32 v10, vcc, s13, v8
	s_mov_b32 s13, 0x7e00000
	s_nop 0
	v_addc_co_u32_e32 v11, vcc, 0, v9, vcc
	global_load_dword v41, v[10:11], off
	v_add_co_u32_e32 v10, vcc, s13, v8
	s_mov_b32 s13, 0x7e1f000
	s_nop 0
	v_addc_co_u32_e32 v11, vcc, 0, v9, vcc
	global_load_dword v42, v[10:11], off offset:3072
	v_add_co_u32_e32 v10, vcc, s13, v8
	s_mov_b32 s13, 0x7e3e000
	s_nop 0
	v_addc_co_u32_e32 v11, vcc, 0, v9, vcc
	global_load_dword v43, v[10:11], off offset:2048
	v_add_co_u32_e32 v10, vcc, s13, v8
	s_mov_b32 s13, 0x7e5d000
	s_nop 0
	v_addc_co_u32_e32 v11, vcc, 0, v9, vcc
	global_load_dword v44, v[10:11], off offset:1024
	v_add_co_u32_e32 v10, vcc, s13, v8
	s_mov_b32 s13, 0x7e7b000
	s_nop 0
	v_addc_co_u32_e32 v11, vcc, 0, v9, vcc
	global_load_dword v45, v[10:11], off
	v_add_co_u32_e32 v10, vcc, s13, v8
	s_mov_b32 s13, 0x7e9a000
	s_nop 0
	v_addc_co_u32_e32 v11, vcc, 0, v9, vcc
	global_load_dword v46, v[10:11], off offset:3072
	v_add_co_u32_e32 v10, vcc, s13, v8
	s_mov_b32 s13, 0x7eb9000
	s_nop 0
	v_addc_co_u32_e32 v11, vcc, 0, v9, vcc
	v_add_co_u32_e32 v8, vcc, s13, v8
	global_load_dword v10, v[10:11], off offset:2048
	s_nop 0
	v_addc_co_u32_e32 v9, vcc, 0, v9, vcc
	global_load_dword v8, v[8:9], off offset:1024
	s_waitcnt vmcnt(30)
	ds_write2_b32 v12, v7, v18 offset1:66
	s_waitcnt vmcnt(28)
	ds_write2_b32 v12, v19, v20 offset0:132 offset1:198
	v_add_u32_e32 v7, 0x400, v12
	s_waitcnt vmcnt(26)
	ds_write2_b32 v7, v21, v22 offset0:8 offset1:74
	s_waitcnt vmcnt(24)
	ds_write2_b32 v7, v23, v24 offset0:140 offset1:206
	v_add_u32_e32 v7, 0x800, v12
	s_waitcnt vmcnt(22)
	ds_write2_b32 v7, v25, v26 offset0:16 offset1:82
	s_waitcnt vmcnt(20)
	ds_write2_b32 v7, v27, v28 offset0:148 offset1:214
	v_add_u32_e32 v7, 0xc00, v12
	s_waitcnt vmcnt(18)
	ds_write2_b32 v7, v29, v30 offset0:24 offset1:90
	s_waitcnt vmcnt(16)
	ds_write2_b32 v7, v31, v32 offset0:156 offset1:222
	v_add_u32_e32 v7, 0x1000, v12
	s_waitcnt vmcnt(14)
	ds_write2_b32 v7, v33, v34 offset0:32 offset1:98
	s_waitcnt vmcnt(12)
	ds_write2_b32 v7, v35, v36 offset0:164 offset1:230
	v_add_u32_e32 v7, 0x1400, v12
	s_waitcnt vmcnt(10)
	ds_write2_b32 v7, v37, v38 offset0:40 offset1:106
	s_waitcnt vmcnt(8)
	ds_write2_b32 v7, v39, v40 offset0:172 offset1:238
	v_add_u32_e32 v7, 0x1800, v12
	s_waitcnt vmcnt(6)
	ds_write2_b32 v7, v41, v42 offset0:48 offset1:114
	s_waitcnt vmcnt(4)
	ds_write2_b32 v7, v43, v44 offset0:180 offset1:246
	v_add_u32_e32 v7, 0x1c00, v12
	s_waitcnt vmcnt(2)
	ds_write2_b32 v7, v45, v46 offset0:56 offset1:122
	s_waitcnt vmcnt(0)
	ds_write2_b32 v7, v10, v8 offset0:188 offset1:254
	s_waitcnt lgkmcnt(0)
	ds_read2_b32 v[20:21], v14 offset0:33 offset1:41
	ds_read2_b32 v[22:23], v14 offset1:8
	ds_read2_b32 v[24:25], v14 offset0:66 offset1:74
	ds_read2_b32 v[26:27], v14 offset0:99 offset1:107
	ds_read2_b32 v[28:29], v14 offset0:132 offset1:140
	ds_read2_b32 v[30:31], v14 offset0:165 offset1:173
	ds_read2_b32 v[32:33], v14 offset0:198 offset1:206
	ds_read2_b32 v[34:35], v14 offset0:231 offset1:239
	s_lshl_b32 s12, s12, 1
	s_add_u32 s12, s9, s12
	v_or_b32_e32 v36, s8, v13
	s_addc_u32 s13, s11, 0
	v_mov_b32_e32 v7, v185
	v_ashrrev_i32_e32 v37, 31, v36
	v_lshl_add_u64 v[18:19], s[12:13], 0, v[6:7]
	v_lshlrev_b64 v[36:37], 12, v[36:37]
	s_waitcnt lgkmcnt(6)
	v_cvt_pk_bf16_f32 v8, v22, v20
	s_waitcnt lgkmcnt(4)
	v_cvt_pk_bf16_f32 v9, v24, v26
	s_waitcnt lgkmcnt(2)
	v_cvt_pk_bf16_f32 v10, v28, v30
	s_waitcnt lgkmcnt(0)
	v_cvt_pk_bf16_f32 v11, v32, v34
	v_lshl_add_u64 v[36:37], v[18:19], 0, v[36:37]
	v_or_b32_e32 v20, s8, v15
	global_store_dwordx4 v[36:37], v[8:11], off
	v_or_b32_e32 v36, s8, v16
	v_ashrrev_i32_e32 v37, 31, v36
	v_cvt_pk_bf16_f32 v8, v23, v21
	v_ashrrev_i32_e32 v21, 31, v20
	v_lshlrev_b64 v[20:21], 12, v[20:21]
	v_cvt_pk_bf16_f32 v9, v25, v27
	v_cvt_pk_bf16_f32 v10, v29, v31
	v_cvt_pk_bf16_f32 v11, v33, v35
	v_lshl_add_u64 v[20:21], v[18:19], 0, v[20:21]
	global_store_dwordx4 v[20:21], v[8:11], off
	ds_read2_b32 v[20:21], v14 offset0:49 offset1:57
	ds_read2_b32 v[22:23], v14 offset0:16 offset1:24
	ds_read2_b32 v[24:25], v14 offset0:82 offset1:90
	ds_read2_b32 v[26:27], v14 offset0:115 offset1:123
	ds_read2_b32 v[28:29], v14 offset0:148 offset1:156
	ds_read2_b32 v[30:31], v14 offset0:181 offset1:189
	ds_read2_b32 v[32:33], v14 offset0:214 offset1:222
	ds_read2_b32 v[34:35], v14 offset0:247 offset1:255
	v_lshlrev_b64 v[36:37], 12, v[36:37]
	s_waitcnt lgkmcnt(6)
	v_cvt_pk_bf16_f32 v8, v22, v20
	s_waitcnt lgkmcnt(4)
	v_cvt_pk_bf16_f32 v9, v24, v26
	s_waitcnt lgkmcnt(2)
	v_cvt_pk_bf16_f32 v10, v28, v30
	s_waitcnt lgkmcnt(0)
	v_cvt_pk_bf16_f32 v11, v32, v34
	v_lshl_add_u64 v[36:37], v[18:19], 0, v[36:37]
	v_or_b32_e32 v20, s8, v17
	global_store_dwordx4 v[36:37], v[8:11], off
	s_nop 1
	v_cvt_pk_bf16_f32 v8, v23, v21
	v_ashrrev_i32_e32 v21, 31, v20
	v_lshlrev_b64 v[20:21], 12, v[20:21]
	v_cvt_pk_bf16_f32 v9, v25, v27
	v_cvt_pk_bf16_f32 v10, v29, v31
	v_cvt_pk_bf16_f32 v11, v33, v35
	v_lshl_add_u64 v[18:19], v[18:19], 0, v[20:21]
	global_store_dwordx4 v[18:19], v[8:11], off
	s_waitcnt lgkmcnt(0)

; __device__ __forceinline__ void transpose_item(const float* W, int ldw, int k0, int n0, bf16* WT, int Kdst, int dst_row0, LAS float* scr, int lane) {
;     ...
;     for (int i = 0; i < 32; ++i) { const int kk = 2 * i + (lane >> 5); tv[i] = W[(size_t)(k0 + kk) * ldw + n0 + (lane & 31)]; }
; __device__ __forceinline__ void phase_wconv(const Frame& F, const Args& a, int l, unsigned char* wt, unsigned char* wth, int part) {
;     ...
;     for (int it = F.gw; it < NITEMS; it += F.NGW) {
;         int r = it;
;         if (r < I_A) {
;             const int m = r / I_FF, q = r % I_FF, f = m / 3, mm = m % 3;
;             if (!((f ? 2 : 1) & part)) continue;
;             if (mm < 2) {
;                 const float* W = a.in[F.z + (f ? 26 : 3) + mm] + (size_t)l * D * FF;
;                 const int kb = q / 176, nb = q % 176, n0 = 32 * nb;
;                 bf16* dst = (bf16*)(f ? wth + WO_UP2 : wt + WO_UP1);
;                 transpose_item(W, FF, 64 * kb, n0, dst, D, (n0 / 128) * 256 + mm * 128 + (n0 % 128), scr, F.lane);
;             } else {
;                 const float* W = a.in[F.z + (f ? 28 : 5)] + (size_t)l * FF * D;
;                 const int kb = q / 64, nb = q % 64, n0 = 32 * nb;
;                 bf16* dst = (bf16*)(f ? wth + WO_DN2 : wt + WO_DN1);
;                 transpose_item(W, D, 64 * kb, n0, dst, FF, n0, scr, F.lane);
.LBB0_749:
	s_andn2_b64 vcc, exec, s[6:7]
	s_cbranch_vccnz .LBB0_743
	s_add_i32 s6, s23, 0xffffbe00
	s_cmp_lt_u32 s6, 0xffff7c01
	s_cbranch_scc1 .LBB0_742
	s_mul_hi_i32 s6, s23, 0x2e8ba2e9
	s_lshr_b32 s7, s6, 31
	s_ashr_i32 s6, s6, 10
	s_add_i32 s6, s6, s7
	s_mul_i32 s7, s6, 0xffffea00
	s_add_i32 s12, s23, s7
	s_mul_hi_i32 s7, s6, 0x55555556
	s_lshr_b32 s8, s7, 31
	s_add_i32 s7, s7, s8
	s_mul_i32 s7, s7, 3
	s_sub_i32 s11, s6, s7
	s_mov_b64 s[6:7], -1
	s_cmp_gt_i32 s11, 1
	v_lshlrev_b32_e32 v184, 2, v0
	v_add_u32_e32 v23, 0x400, v12
	v_add_u32_e32 v22, 0x800, v12
	v_add_u32_e32 v21, 0xc00, v12
	v_add_u32_e32 v20, 0x1000, v12
	v_add_u32_e32 v19, 0x1400, v12
	v_add_u32_e32 v18, 0x1800, v12
	v_add_u32_e32 v7, 0x1c00, v12
	s_cbranch_scc0 .LBB0_753
	s_bfe_u32 s6, s12, 0x60019
	s_add_i32 s6, s12, s6
	s_sext_i32_i16 s7, s6
	s_and_b32 s6, s6, 0xffc0
	s_load_dwordx2 s[14:15], s[4:5], 0x28
	s_sub_i32 s6, s12, s6
	s_sext_i32_i16 s6, s6
	s_lshl_b32 s6, s6, 5
	s_and_b32 s8, s7, 0xffffffc0
	s_ashr_i32 s7, s6, 31
	s_lshl_b64 s[16:17], s[6:7], 2
	s_waitcnt lgkmcnt(0)
	s_add_u32 s14, s14, s16
	v_or_b32_e32 v8, s8, v1
	s_addc_u32 s15, s15, s17
	v_lshl_add_u64 v[10:11], s[14:15], 0, v[184:185]
	s_mov_b64 s[14:15], 0x2c00000
	v_ashrrev_i32_e32 v9, 31, v8
	v_lshl_add_u64 v[10:11], v[10:11], 0, s[14:15]
	v_lshlrev_b64 v[24:25], 13, v[8:9]
	v_lshl_add_u64 v[24:25], v[10:11], 0, v[24:25]
	global_load_dword v26, v[24:25], off
	v_or_b32_e32 v24, 2, v8
	v_ashrrev_i32_e32 v25, 31, v24
	v_lshlrev_b64 v[24:25], 13, v[24:25]
	v_lshl_add_u64 v[24:25], v[10:11], 0, v[24:25]
	global_load_dword v27, v[24:25], off
	v_or_b32_e32 v24, 4, v8
	v_ashrrev_i32_e32 v25, 31, v24
	v_lshlrev_b64 v[24:25], 13, v[24:25]
	v_lshl_add_u64 v[24:25], v[10:11], 0, v[24:25]
	global_load_dword v28, v[24:25], off
	v_or_b32_e32 v24, 6, v8
	v_ashrrev_i32_e32 v25, 31, v24
	v_lshlrev_b64 v[24:25], 13, v[24:25]
	v_lshl_add_u64 v[24:25], v[10:11], 0, v[24:25]
	global_load_dword v29, v[24:25], off
	v_or_b32_e32 v24, 8, v8
	v_ashrrev_i32_e32 v25, 31, v24
	v_lshlrev_b64 v[24:25], 13, v[24:25]
	v_lshl_add_u64 v[24:25], v[10:11], 0, v[24:25]
	global_load_dword v30, v[24:25], off
	v_or_b32_e32 v24, 10, v8
	v_ashrrev_i32_e32 v25, 31, v24
	v_lshlrev_b64 v[24:25], 13, v[24:25]
	v_lshl_add_u64 v[24:25], v[10:11], 0, v[24:25]
	global_load_dword v31, v[24:25], off
	v_or_b32_e32 v24, 12, v8
	v_ashrrev_i32_e32 v25, 31, v24
	v_lshlrev_b64 v[24:25], 13, v[24:25]
	v_lshl_add_u64 v[24:25], v[10:11], 0, v[24:25]
	global_load_dword v32, v[24:25], off
	v_or_b32_e32 v24, 14, v8
	v_ashrrev_i32_e32 v25, 31, v24
	v_lshlrev_b64 v[24:25], 13, v[24:25]
	v_lshl_add_u64 v[24:25], v[10:11], 0, v[24:25]
	global_load_dword v33, v[24:25], off
	s_waitcnt vmcnt(2)
	v_or_b32_e32 v24, 16, v8
	v_ashrrev_i32_e32 v25, 31, v24
	v_lshlrev_b64 v[24:25], 13, v[24:25]
	v_lshl_add_u64 v[24:25], v[10:11], 0, v[24:25]
	global_load_dword v34, v[24:25], off
	v_or_b32_e32 v24, 18, v8
	v_ashrrev_i32_e32 v25, 31, v24
	v_lshlrev_b64 v[24:25], 13, v[24:25]
	v_lshl_add_u64 v[24:25], v[10:11], 0, v[24:25]
	global_load_dword v35, v[24:25], off
	v_or_b32_e32 v24, 20, v8
	v_ashrrev_i32_e32 v25, 31, v24
	v_lshlrev_b64 v[24:25], 13, v[24:25]
	v_lshl_add_u64 v[24:25], v[10:11], 0, v[24:25]
	global_load_dword v36, v[24:25], off
	v_or_b32_e32 v24, 22, v8
	v_ashrrev_i32_e32 v25, 31, v24
	v_lshlrev_b64 v[24:25], 13, v[24:25]
	v_lshl_add_u64 v[24:25], v[10:11], 0, v[24:25]
	global_load_dword v37, v[24:25], off
	v_or_b32_e32 v24, 24, v8
	v_ashrrev_i32_e32 v25, 31, v24
	v_lshlrev_b64 v[24:25], 13, v[24:25]
	v_lshl_add_u64 v[24:25], v[10:11], 0, v[24:25]
	global_load_dword v38, v[24:25], off
	v_or_b32_e32 v24, 26, v8
	v_ashrrev_i32_e32 v25, 31, v24
	v_lshlrev_b64 v[24:25], 13, v[24:25]
	v_lshl_add_u64 v[24:25], v[10:11], 0, v[24:25]
	global_load_dword v39, v[24:25], off
	v_or_b32_e32 v24, 28, v8
	v_ashrrev_i32_e32 v25, 31, v24
	v_lshlrev_b64 v[24:25], 13, v[24:25]
	v_lshl_add_u64 v[24:25], v[10:11], 0, v[24:25]
	global_load_dword v40, v[24:25], off
	v_or_b32_e32 v24, 30, v8
	v_ashrrev_i32_e32 v25, 31, v24
	v_lshlrev_b64 v[24:25], 13, v[24:25]
	v_lshl_add_u64 v[24:25], v[10:11], 0, v[24:25]
	global_load_dword v41, v[24:25], off
	s_waitcnt vmcnt(2)
	v_or_b32_e32 v24, 32, v8
	v_ashrrev_i32_e32 v25, 31, v24
	v_lshlrev_b64 v[24:25], 13, v[24:25]
	v_lshl_add_u64 v[24:25], v[10:11], 0, v[24:25]
	global_load_dword v42, v[24:25], off
	v_or_b32_e32 v24, 34, v8
	v_ashrrev_i32_e32 v25, 31, v24
	v_lshlrev_b64 v[24:25], 13, v[24:25]
	v_lshl_add_u64 v[24:25], v[10:11], 0, v[24:25]
	global_load_dword v43, v[24:25], off
	v_or_b32_e32 v24, 36, v8
	v_ashrrev_i32_e32 v25, 31, v24
	v_lshlrev_b64 v[24:25], 13, v[24:25]
	v_lshl_add_u64 v[24:25], v[10:11], 0, v[24:25]
	global_load_dword v44, v[24:25], off
	v_or_b32_e32 v24, 38, v8
	v_ashrrev_i32_e32 v25, 31, v24
	v_lshlrev_b64 v[24:25], 13, v[24:25]
	v_lshl_add_u64 v[24:25], v[10:11], 0, v[24:25]
	global_load_dword v45, v[24:25], off
	v_or_b32_e32 v24, 40, v8
	v_ashrrev_i32_e32 v25, 31, v24
	v_lshlrev_b64 v[24:25], 13, v[24:25]
	v_lshl_add_u64 v[24:25], v[10:11], 0, v[24:25]
	global_load_dword v46, v[24:25], off
	v_or_b32_e32 v24, 42, v8
	v_ashrrev_i32_e32 v25, 31, v24
	v_lshlrev_b64 v[24:25], 13, v[24:25]
	v_lshl_add_u64 v[24:25], v[10:11], 0, v[24:25]
	global_load_dword v47, v[24:25], off
	v_or_b32_e32 v24, 44, v8
	v_ashrrev_i32_e32 v25, 31, v24
	v_lshlrev_b64 v[24:25], 13, v[24:25]
	v_lshl_add_u64 v[24:25], v[10:11], 0, v[24:25]
	global_load_dword v48, v[24:25], off
	v_or_b32_e32 v24, 46, v8
	v_ashrrev_i32_e32 v25, 31, v24
	v_lshlrev_b64 v[24:25], 13, v[24:25]
	v_lshl_add_u64 v[24:25], v[10:11], 0, v[24:25]
	global_load_dword v49, v[24:25], off
	s_waitcnt vmcnt(2)
; #define LAS __attribute__((address_space(3)))
; #define LDS_WAIT() asm volatile("s_waitcnt lgkmcnt(0)" ::: "memory")
; __device__ __forceinline__ unsigned pk2(float lo, float hi) { return cvt_pk_bf16(lo, hi); }
; __device__ __forceinline__ void transpose_item(const float* W, int ldw, int k0, int n0, bf16* WT, int Kdst, int dst_row0, LAS float* scr, int lane) {
;     ...
;     for (int i = 0; i < 32; ++i) { const int kk = 2 * i + (lane >> 5); scr[kk * 33 + (lane & 31)] = tv[i]; }
;     LDS_WAIT(); asm volatile("" ::: "memory");
;     const int c = lane & 7;
; #pragma unroll
;     for (int j = 0; j < 4; ++j) { const int n = (lane >> 3) + 8 * j; const LAS float* s = scr + (8 * c) * 33 + n;
;         v4u o; o.x = pk2(s[0 * 33], s[1 * 33]); o.y = pk2(s[2 * 33], s[3 * 33]); o.z = pk2(s[4 * 33], s[5 * 33]); o.w = pk2(s[6 * 33], s[7 * 33]);
;         *(v4u*)(WT + (size_t)(dst_row0 + n) * Kdst + k0 + 8 * c) = o; }
;     LDS_WAIT(); asm volatile("" ::: "memory");
	v_or_b32_e32 v24, 48, v8
	v_ashrrev_i32_e32 v25, 31, v24
	v_lshlrev_b64 v[24:25], 13, v[24:25]
	v_lshl_add_u64 v[24:25], v[10:11], 0, v[24:25]
	global_load_dword v50, v[24:25], off
	v_or_b32_e32 v24, 50, v8
	v_ashrrev_i32_e32 v25, 31, v24
	v_lshlrev_b64 v[24:25], 13, v[24:25]
	v_lshl_add_u64 v[24:25], v[10:11], 0, v[24:25]
	global_load_dword v51, v[24:25], off
	v_or_b32_e32 v24, 52, v8
	v_ashrrev_i32_e32 v25, 31, v24
	v_lshlrev_b64 v[24:25], 13, v[24:25]
	v_lshl_add_u64 v[24:25], v[10:11], 0, v[24:25]
	global_load_dword v52, v[24:25], off
	v_or_b32_e32 v24, 54, v8
	v_ashrrev_i32_e32 v25, 31, v24
	v_lshlrev_b64 v[24:25], 13, v[24:25]
	v_lshl_add_u64 v[24:25], v[10:11], 0, v[24:25]
	global_load_dword v53, v[24:25], off
	v_or_b32_e32 v24, 56, v8
	v_ashrrev_i32_e32 v25, 31, v24
	v_lshlrev_b64 v[24:25], 13, v[24:25]
	v_lshl_add_u64 v[24:25], v[10:11], 0, v[24:25]
	global_load_dword v54, v[24:25], off
	v_or_b32_e32 v24, 58, v8
	v_ashrrev_i32_e32 v25, 31, v24
	v_lshlrev_b64 v[24:25], 13, v[24:25]
	v_lshl_add_u64 v[24:25], v[10:11], 0, v[24:25]
	global_load_dword v55, v[24:25], off
	v_or_b32_e32 v24, 60, v8
	v_or_b32_e32 v8, 62, v8
	v_ashrrev_i32_e32 v25, 31, v24
	v_ashrrev_i32_e32 v9, 31, v8
	v_lshlrev_b64 v[24:25], 13, v[24:25]
	v_lshlrev_b64 v[8:9], 13, v[8:9]
	v_lshl_add_u64 v[24:25], v[10:11], 0, v[24:25]
	v_lshl_add_u64 v[8:9], v[10:11], 0, v[8:9]
	global_load_dword v24, v[24:25], off
	s_ashr_i32 s9, s8, 31
	global_load_dword v8, v[8:9], off
	s_waitcnt vmcnt(30)
	ds_write2_b32 v12, v26, v27 offset1:66
	s_waitcnt vmcnt(28)
	ds_write2_b32 v12, v28, v29 offset0:132 offset1:198
	s_waitcnt vmcnt(26)
	ds_write2_b32 v23, v30, v31 offset0:8 offset1:74
	s_waitcnt vmcnt(24)
	ds_write2_b32 v23, v32, v33 offset0:140 offset1:206
	s_waitcnt vmcnt(22)
	ds_write2_b32 v22, v34, v35 offset0:16 offset1:82
	s_waitcnt vmcnt(20)
	ds_write2_b32 v22, v36, v37 offset0:148 offset1:214
	s_waitcnt vmcnt(18)
	ds_write2_b32 v21, v38, v39 offset0:24 offset1:90
	s_waitcnt vmcnt(16)
	ds_write2_b32 v21, v40, v41 offset0:156 offset1:222
	s_waitcnt vmcnt(14)
	ds_write2_b32 v20, v42, v43 offset0:32 offset1:98
	s_waitcnt vmcnt(12)
	ds_write2_b32 v20, v44, v45 offset0:164 offset1:230
	s_waitcnt vmcnt(10)
	ds_write2_b32 v19, v46, v47 offset0:40 offset1:106
	s_waitcnt vmcnt(8)
	ds_write2_b32 v19, v48, v49 offset0:172 offset1:238
	s_waitcnt vmcnt(6)
	ds_write2_b32 v18, v50, v51 offset0:48 offset1:114
	s_waitcnt vmcnt(4)
	ds_write2_b32 v18, v52, v53 offset0:180 offset1:246
	s_waitcnt vmcnt(2)
	ds_write2_b32 v7, v54, v55 offset0:56 offset1:122
	s_waitcnt vmcnt(0)
	ds_write2_b32 v7, v24, v8 offset0:188 offset1:254
	s_waitcnt lgkmcnt(0)
	ds_read2_b32 v[26:27], v14 offset0:33 offset1:41
	ds_read2_b32 v[28:29], v14 offset1:8
	ds_read2_b32 v[30:31], v14 offset0:66 offset1:74
	ds_read2_b32 v[32:33], v14 offset0:99 offset1:107
	ds_read2_b32 v[34:35], v14 offset0:132 offset1:140
	ds_read2_b32 v[36:37], v14 offset0:165 offset1:173
	ds_read2_b32 v[38:39], v14 offset0:198 offset1:206
	ds_read2_b32 v[40:41], v14 offset0:231 offset1:239
	v_lshl_add_u64 v[24:25], s[8:9], 1, v[2:3]
	s_waitcnt lgkmcnt(6)
	v_cvt_pk_bf16_f32 v8, v28, v26
	v_or_b32_e32 v26, s6, v13
	v_mul_i32_i24_e32 v42, 0x2c00, v26
	v_ashrrev_i32_e32 v43, 31, v42
	v_or_b32_e32 v26, s6, v15
	s_waitcnt lgkmcnt(4)
	v_cvt_pk_bf16_f32 v9, v30, v32
	s_waitcnt lgkmcnt(2)
	v_cvt_pk_bf16_f32 v10, v34, v36
	s_waitcnt lgkmcnt(0)
	v_cvt_pk_bf16_f32 v11, v38, v40
	v_lshl_add_u64 v[42:43], v[24:25], 0, v[42:43]
	v_mul_i32_i24_e32 v26, 0x2c00, v26
	global_store_dwordx4 v[42:43], v[8:11], off
	s_nop 1
	v_cvt_pk_bf16_f32 v8, v29, v27
	v_ashrrev_i32_e32 v27, 31, v26
	v_cvt_pk_bf16_f32 v9, v31, v33
	v_cvt_pk_bf16_f32 v10, v35, v37
	v_cvt_pk_bf16_f32 v11, v39, v41
	v_lshl_add_u64 v[26:27], v[24:25], 0, v[26:27]
	global_store_dwordx4 v[26:27], v[8:11], off
	ds_read2_b32 v[26:27], v14 offset0:16 offset1:24
	ds_read2_b32 v[28:29], v14 offset0:49 offset1:57
	ds_read2_b32 v[30:31], v14 offset0:82 offset1:90
	ds_read2_b32 v[32:33], v14 offset0:115 offset1:123
	ds_read2_b32 v[34:35], v14 offset0:148 offset1:156
	ds_read2_b32 v[36:37], v14 offset0:181 offset1:189
	ds_read2_b32 v[38:39], v14 offset0:214 offset1:222
	ds_read2_b32 v[40:41], v14 offset0:247 offset1:255
	s_waitcnt lgkmcnt(6)
	v_cvt_pk_bf16_f32 v8, v26, v28
	v_or_b32_e32 v26, s6, v16
	v_mul_i32_i24_e32 v42, 0x2c00, v26
	v_ashrrev_i32_e32 v43, 31, v42
	v_or_b32_e32 v26, s6, v17
	s_waitcnt lgkmcnt(4)
	v_cvt_pk_bf16_f32 v9, v30, v32
	s_waitcnt lgkmcnt(2)
	v_cvt_pk_bf16_f32 v10, v34, v36
	s_waitcnt lgkmcnt(0)
	v_cvt_pk_bf16_f32 v11, v38, v40
	v_lshl_add_u64 v[42:43], v[24:25], 0, v[42:43]
	v_mul_i32_i24_e32 v26, 0x2c00, v26
	global_store_dwordx4 v[42:43], v[8:11], off
	s_mov_b64 s[6:7], 0
	s_nop 0
	v_cvt_pk_bf16_f32 v8, v27, v29
	v_ashrrev_i32_e32 v27, 31, v26
	v_cvt_pk_bf16_f32 v9, v31, v33
	v_cvt_pk_bf16_f32 v10, v35, v37
	v_cvt_pk_bf16_f32 v11, v39, v41
	v_lshl_add_u64 v[24:25], v[24:25], 0, v[26:27]
	global_store_dwordx4 v[24:25], v[8:11], off
	s_waitcnt lgkmcnt(0)
; __device__ __forceinline__ void transpose_item(const float* W, int ldw, int k0, int n0, bf16* WT, int Kdst, int dst_row0, LAS float* scr, int lane) {
;     ...
;     for (int i = 0; i < 32; ++i) { const int kk = 2 * i + (lane >> 5); tv[i] = W[(size_t)(k0 + kk) * ldw + n0 + (lane & 31)]; }
; __device__ __forceinline__ void phase_wconv(const Frame& F, const Args& a, int l, unsigned char* wt, unsigned char* wth, int part) {
;     ...
;             if (mm < 2) {
;                 const float* W = a.in[F.z + (f ? 26 : 3) + mm] + (size_t)l * D * FF;
;                 const int kb = q / 176, nb = q % 176, n0 = 32 * nb;
;                 bf16* dst = (bf16*)(f ? wth + WO_UP2 : wt + WO_UP1);
;                 transpose_item(W, FF, 64 * kb, n0, dst, D, (n0 / 128) * 256 + mm * 128 + (n0 % 128), scr, F.lane);
.LBB0_753:
	s_andn2_b64 vcc, exec, s[6:7]
	s_cbranch_vccnz .LBB0_742
	s_add_i32 s6, s10, s11
	s_ashr_i32 s7, s6, 31
	s_lshl_b64 s[6:7], s[6:7], 3
	v_readlane_b32 s8, v254, 1
	v_readlane_b32 s9, v254, 2
	s_add_u32 s6, s8, s6
	s_addc_u32 s7, s9, s7
	s_load_dwordx2 s[14:15], s[6:7], 0x0
	s_mul_i32 s6, s12, 0xba3
	s_lshr_b32 s7, s6, 31
	s_ashr_i32 s6, s6, 19
	s_add_i32 s6, s6, s7
	s_mul_i32 s7, s6, 0xb0
	s_sub_i32 s7, s12, s7
	s_sext_i32_i16 s8, s7
	s_bfe_u32 s9, s8, 0x2001d
	s_lshl_b32 s12, s8, 5
	s_add_i32 s7, s7, s9
	s_bfe_u32 s8, s8, 0x70013
	s_sext_i32_i16 s7, s7
	s_add_i32 s8, s12, s8
	s_lshl_b32 s7, s7, 6
	s_and_b32 s8, s8, 0xff80
	s_and_b32 s7, s7, 0xffffff00
	s_lshl_b32 s9, s11, 7
	s_sub_i32 s8, s12, s8
	s_add_i32 s7, s7, s9
	s_sext_i32_i16 s8, s8
	s_ashr_i32 s13, s12, 31
	s_lshl_b32 s6, s6, 6
	s_add_i32 s8, s7, s8
	s_lshl_b64 s[12:13], s[12:13], 2
	v_or_b32_e32 v10, s6, v1
	s_waitcnt lgkmcnt(0)
	s_add_u32 s12, s14, s12
	s_addc_u32 s13, s15, s13
	v_mul_i32_i24_e32 v10, 0x5800, v10
	v_lshl_add_u64 v[8:9], s[12:13], 0, v[184:185]
	v_ashrrev_i32_e32 v11, 31, v10
	v_lshl_add_u64 v[8:9], v[8:9], 0, v[10:11]
	s_mov_b32 s7, 0x2c00000
	v_add_co_u32_e32 v10, vcc, s7, v8
	s_mov_b32 s7, 0x2c0b000
	s_nop 0
	v_addc_co_u32_e32 v11, vcc, 0, v9, vcc
	global_load_dword v24, v[10:11], off
	v_add_co_u32_e32 v10, vcc, s7, v8
	s_mov_b32 s7, 0x2c16000
	s_nop 0
	v_addc_co_u32_e32 v11, vcc, 0, v9, vcc
	global_load_dword v25, v[10:11], off
	v_add_co_u32_e32 v10, vcc, s7, v8
	s_mov_b32 s7, 0x2c21000
	s_nop 0
	v_addc_co_u32_e32 v11, vcc, 0, v9, vcc
	global_load_dword v26, v[10:11], off
	v_add_co_u32_e32 v10, vcc, s7, v8
	s_mov_b32 s7, 0x2c2c000
	s_nop 0
	v_addc_co_u32_e32 v11, vcc, 0, v9, vcc
	global_load_dword v27, v[10:11], off
	v_add_co_u32_e32 v10, vcc, s7, v8
	s_mov_b32 s7, 0x2c37000
	s_nop 0
	v_addc_co_u32_e32 v11, vcc, 0, v9, vcc
	global_load_dword v28, v[10:11], off
	v_add_co_u32_e32 v10, vcc, s7, v8
	s_mov_b32 s7, 0x2c42000
	s_nop 0
	v_addc_co_u32_e32 v11, vcc, 0, v9, vcc
	global_load_dword v29, v[10:11], off
	v_add_co_u32_e32 v10, vcc, s7, v8
	s_mov_b32 s7, 0x2c4d000
	s_nop 0
	v_addc_co_u32_e32 v11, vcc, 0, v9, vcc
	global_load_dword v30, v[10:11], off
	v_add_co_u32_e32 v10, vcc, s7, v8
	s_mov_b32 s7, 0x2c58000
	s_nop 0
	v_addc_co_u32_e32 v11, vcc, 0, v9, vcc
	global_load_dword v31, v[10:11], off
	s_waitcnt vmcnt(2)
	v_add_co_u32_e32 v10, vcc, s7, v8
	s_mov_b32 s7, 0x2c63000
	s_nop 0
	v_addc_co_u32_e32 v11, vcc, 0, v9, vcc
	global_load_dword v32, v[10:11], off
	v_add_co_u32_e32 v10, vcc, s7, v8
	s_mov_b32 s7, 0x2c6e000
	s_nop 0
	v_addc_co_u32_e32 v11, vcc, 0, v9, vcc
	global_load_dword v33, v[10:11], off
	v_add_co_u32_e32 v10, vcc, s7, v8
	s_mov_b32 s7, 0x2c79000
	s_nop 0
	v_addc_co_u32_e32 v11, vcc, 0, v9, vcc
	global_load_dword v34, v[10:11], off
	v_add_co_u32_e32 v10, vcc, s7, v8
	s_mov_b32 s7, 0x2c84000
	s_nop 0
	v_addc_co_u32_e32 v11, vcc, 0, v9, vcc
	global_load_dword v35, v[10:11], off
	v_add_co_u32_e32 v10, vcc, s7, v8
	s_mov_b32 s7, 0x2c8f000
	s_nop 0
	v_addc_co_u32_e32 v11, vcc, 0, v9, vcc
	global_load_dword v36, v[10:11], off
	v_add_co_u32_e32 v10, vcc, s7, v8
	s_mov_b32 s7, 0x2c9a000
	s_nop 0
	v_addc_co_u32_e32 v11, vcc, 0, v9, vcc
	global_load_dword v37, v[10:11], off
	v_add_co_u32_e32 v10, vcc, s7, v8
	s_mov_b32 s7, 0x2ca5000
	s_nop 0
	v_addc_co_u32_e32 v11, vcc, 0, v9, vcc
	global_load_dword v38, v[10:11], off
	v_add_co_u32_e32 v10, vcc, s7, v8
	s_mov_b32 s7, 0x2cb0000
	s_nop 0
	v_addc_co_u32_e32 v11, vcc, 0, v9, vcc
	global_load_dword v39, v[10:11], off
	s_waitcnt vmcnt(2)
	v_add_co_u32_e32 v10, vcc, s7, v8
	s_mov_b32 s7, 0x2cbb000
	s_nop 0
	v_addc_co_u32_e32 v11, vcc, 0, v9, vcc
	global_load_dword v40, v[10:11], off
	v_add_co_u32_e32 v10, vcc, s7, v8
	s_mov_b32 s7, 0x2cc6000
	s_nop 0
	v_addc_co_u32_e32 v11, vcc, 0, v9, vcc
	global_load_dword v41, v[10:11], off
	v_add_co_u32_e32 v10, vcc, s7, v8
	s_mov_b32 s7, 0x2cd1000
	s_nop 0
	v_addc_co_u32_e32 v11, vcc, 0, v9, vcc
	global_load_dword v42, v[10:11], off
	v_add_co_u32_e32 v10, vcc, s7, v8
	s_mov_b32 s7, 0x2cdc000
	s_nop 0
	v_addc_co_u32_e32 v11, vcc, 0, v9, vcc
	global_load_dword v43, v[10:11], off
	v_add_co_u32_e32 v10, vcc, s7, v8
	s_mov_b32 s7, 0x2ce7000
	s_nop 0
	v_addc_co_u32_e32 v11, vcc, 0, v9, vcc
	global_load_dword v44, v[10:11], off
	v_add_co_u32_e32 v10, vcc, s7, v8
	s_mov_b32 s7, 0x2cf2000
	s_nop 0
	v_addc_co_u32_e32 v11, vcc, 0, v9, vcc
	global_load_dword v45, v[10:11], off
	v_add_co_u32_e32 v10, vcc, s7, v8
	s_mov_b32 s7, 0x2cfd000
	s_nop 0
	v_addc_co_u32_e32 v11, vcc, 0, v9, vcc
	global_load_dword v46, v[10:11], off
	v_add_co_u32_e32 v10, vcc, s7, v8
	s_mov_b32 s7, 0x2d08000
	s_nop 0
	v_addc_co_u32_e32 v11, vcc, 0, v9, vcc
	global_load_dword v47, v[10:11], off
	s_waitcnt vmcnt(2)
; #define LAS __attribute__((address_space(3)))
; #define LDS_WAIT() asm volatile("s_waitcnt lgkmcnt(0)" ::: "memory")
; __device__ __forceinline__ unsigned pk2(float lo, float hi) { return cvt_pk_bf16(lo, hi); }
; __device__ __forceinline__ void transpose_item(const float* W, int ldw, int k0, int n0, bf16* WT, int Kdst, int dst_row0, LAS float* scr, int lane) {
;     ...
;     for (int i = 0; i < 32; ++i) { const int kk = 2 * i + (lane >> 5); scr[kk * 33 + (lane & 31)] = tv[i]; }
;     LDS_WAIT(); asm volatile("" ::: "memory");
;     const int c = lane & 7;
; #pragma unroll
;     for (int j = 0; j < 4; ++j) { const int n = (lane >> 3) + 8 * j; const LAS float* s = scr + (8 * c) * 33 + n;
;         v4u o; o.x = pk2(s[0 * 33], s[1 * 33]); o.y = pk2(s[2 * 33], s[3 * 33]); o.z = pk2(s[4 * 33], s[5 * 33]); o.w = pk2(s[6 * 33], s[7 * 33]);
;         *(v4u*)(WT + (size_t)(dst_row0 + n) * Kdst + k0 + 8 * c) = o; }
;     LDS_WAIT(); asm volatile("" ::: "memory");
	v_add_co_u32_e32 v10, vcc, s7, v8
	s_mov_b32 s7, 0x2d13000
	s_nop 0
	v_addc_co_u32_e32 v11, vcc, 0, v9, vcc
	global_load_dword v48, v[10:11], off
	v_add_co_u32_e32 v10, vcc, s7, v8
	s_mov_b32 s7, 0x2d1e000
	s_nop 0
	v_addc_co_u32_e32 v11, vcc, 0, v9, vcc
	global_load_dword v49, v[10:11], off
	v_add_co_u32_e32 v10, vcc, s7, v8
	s_mov_b32 s7, 0x2d29000
	s_nop 0
	v_addc_co_u32_e32 v11, vcc, 0, v9, vcc
	global_load_dword v50, v[10:11], off
	v_add_co_u32_e32 v10, vcc, s7, v8
	s_mov_b32 s7, 0x2d34000
	s_nop 0
	v_addc_co_u32_e32 v11, vcc, 0, v9, vcc
	global_load_dword v51, v[10:11], off
	v_add_co_u32_e32 v10, vcc, s7, v8
	s_mov_b32 s7, 0x2d3f000
	s_nop 0
	v_addc_co_u32_e32 v11, vcc, 0, v9, vcc
	global_load_dword v52, v[10:11], off
	v_add_co_u32_e32 v10, vcc, s7, v8
	s_mov_b32 s7, 0x2d4a000
	s_nop 0
	v_addc_co_u32_e32 v11, vcc, 0, v9, vcc
	global_load_dword v53, v[10:11], off
	v_add_co_u32_e32 v10, vcc, s7, v8
	s_mov_b32 s7, 0x2d55000
	s_nop 0
	v_addc_co_u32_e32 v11, vcc, 0, v9, vcc
	v_add_co_u32_e32 v8, vcc, s7, v8
	global_load_dword v10, v[10:11], off
	s_nop 0
	v_addc_co_u32_e32 v9, vcc, 0, v9, vcc
	global_load_dword v8, v[8:9], off
	s_waitcnt vmcnt(30)
	ds_write2_b32 v12, v24, v25 offset1:66
	s_waitcnt vmcnt(28)
	ds_write2_b32 v12, v26, v27 offset0:132 offset1:198
	s_waitcnt vmcnt(26)
	ds_write2_b32 v23, v28, v29 offset0:8 offset1:74
	s_waitcnt vmcnt(24)
	ds_write2_b32 v23, v30, v31 offset0:140 offset1:206
	s_waitcnt vmcnt(22)
	ds_write2_b32 v22, v32, v33 offset0:16 offset1:82
	s_waitcnt vmcnt(20)
	ds_write2_b32 v22, v34, v35 offset0:148 offset1:214
	s_waitcnt vmcnt(18)
	ds_write2_b32 v21, v36, v37 offset0:24 offset1:90
	s_waitcnt vmcnt(16)
	ds_write2_b32 v21, v38, v39 offset0:156 offset1:222
	s_waitcnt vmcnt(14)
	ds_write2_b32 v20, v40, v41 offset0:32 offset1:98
	s_waitcnt vmcnt(12)
	ds_write2_b32 v20, v42, v43 offset0:164 offset1:230
	s_waitcnt vmcnt(10)
	ds_write2_b32 v19, v44, v45 offset0:40 offset1:106
	s_waitcnt vmcnt(8)
	ds_write2_b32 v19, v46, v47 offset0:172 offset1:238
	s_waitcnt vmcnt(6)
	ds_write2_b32 v18, v48, v49 offset0:48 offset1:114
	s_waitcnt vmcnt(4)
	ds_write2_b32 v18, v50, v51 offset0:180 offset1:246
	s_waitcnt vmcnt(2)
	ds_write2_b32 v7, v52, v53 offset0:56 offset1:122
	s_waitcnt vmcnt(0)
	ds_write2_b32 v7, v10, v8 offset0:188 offset1:254
	s_waitcnt lgkmcnt(0)
	ds_read2_b32 v[20:21], v14 offset0:33 offset1:41
	ds_read2_b32 v[22:23], v14 offset1:8
	ds_read2_b32 v[24:25], v14 offset0:66 offset1:74
	ds_read2_b32 v[26:27], v14 offset0:99 offset1:107
	ds_read2_b32 v[28:29], v14 offset0:132 offset1:140
	ds_read2_b32 v[30:31], v14 offset0:165 offset1:173
	ds_read2_b32 v[32:33], v14 offset0:198 offset1:206
	ds_read2_b32 v[34:35], v14 offset0:231 offset1:239
	v_or_b32_e32 v36, s8, v13
	s_ashr_i32 s7, s6, 31
	v_ashrrev_i32_e32 v37, 31, v36
	v_lshl_add_u64 v[18:19], s[6:7], 1, v[4:5]
	v_lshlrev_b64 v[36:37], 12, v[36:37]
	s_waitcnt lgkmcnt(6)
	v_cvt_pk_bf16_f32 v8, v22, v20
	s_waitcnt lgkmcnt(4)
	v_cvt_pk_bf16_f32 v9, v24, v26
	s_waitcnt lgkmcnt(2)
	v_cvt_pk_bf16_f32 v10, v28, v30
	s_waitcnt lgkmcnt(0)
	v_cvt_pk_bf16_f32 v11, v32, v34
	v_lshl_add_u64 v[36:37], v[18:19], 0, v[36:37]
	v_or_b32_e32 v20, s8, v15
	global_store_dwordx4 v[36:37], v[8:11], off
	v_or_b32_e32 v36, s8, v16
	v_ashrrev_i32_e32 v37, 31, v36
	v_cvt_pk_bf16_f32 v8, v23, v21
	v_ashrrev_i32_e32 v21, 31, v20
	v_lshlrev_b64 v[20:21], 12, v[20:21]
	v_cvt_pk_bf16_f32 v9, v25, v27
	v_cvt_pk_bf16_f32 v10, v29, v31
	v_cvt_pk_bf16_f32 v11, v33, v35
	v_lshl_add_u64 v[20:21], v[18:19], 0, v[20:21]
	global_store_dwordx4 v[20:21], v[8:11], off
	ds_read2_b32 v[20:21], v14 offset0:49 offset1:57
	ds_read2_b32 v[22:23], v14 offset0:16 offset1:24
	ds_read2_b32 v[24:25], v14 offset0:82 offset1:90
	ds_read2_b32 v[26:27], v14 offset0:115 offset1:123
	ds_read2_b32 v[28:29], v14 offset0:148 offset1:156
	ds_read2_b32 v[30:31], v14 offset0:181 offset1:189
	ds_read2_b32 v[32:33], v14 offset0:214 offset1:222
	ds_read2_b32 v[34:35], v14 offset0:247 offset1:255
	v_lshlrev_b64 v[36:37], 12, v[36:37]
	s_waitcnt lgkmcnt(6)
	v_cvt_pk_bf16_f32 v8, v22, v20
	s_waitcnt lgkmcnt(4)
	v_cvt_pk_bf16_f32 v9, v24, v26
	s_waitcnt lgkmcnt(2)
	v_cvt_pk_bf16_f32 v10, v28, v30
	s_waitcnt lgkmcnt(0)
	v_cvt_pk_bf16_f32 v11, v32, v34
	v_lshl_add_u64 v[36:37], v[18:19], 0, v[36:37]
	v_or_b32_e32 v20, s8, v17
	global_store_dwordx4 v[36:37], v[8:11], off
	s_nop 1
	v_cvt_pk_bf16_f32 v8, v23, v21
	v_ashrrev_i32_e32 v21, 31, v20
	v_lshlrev_b64 v[20:21], 12, v[20:21]
	v_cvt_pk_bf16_f32 v9, v25, v27
	v_cvt_pk_bf16_f32 v10, v29, v31
	v_cvt_pk_bf16_f32 v11, v33, v35
	v_lshl_add_u64 v[18:19], v[18:19], 0, v[20:21]
	global_store_dwordx4 v[18:19], v[8:11], off
	s_waitcnt lgkmcnt(0)
	s_branch .LBB0_742
